# scan compute step: 16 output stores use precomputed per-lane offsets + SGPR base (64 VALU address instructions removed per step)
# speedup vs baseline: 1.0025x; 1.0025x over previous
; #define LAS __attribute__((address_space(3)))
; #define U_LOAD(nn) do { const unsigned char* tr_ = P.tr + (size_t)((b << 8) | ((nn) << 3) | h) * TR_SZ; \
;             _Pragma("unroll") for (int mt_ = 0; mt_ < 4; ++mt_) ubn[mt_] = *(const f32x4*)(tr_ + (oU + (unsigned)mt_ * 1024u)); } while (0)
; __device__ __forceinline__ void scan_bh(LAS unsigned char* lds, const ScanP& P, int b, int h, int half, int tid, int lane, int wave) {
;     ...
;         f32x4 S[8];
; #pragma unroll
;         for (int i = 0; i < 8; ++i) S[i] = (f32x4){0.f, 0.f, 0.f, 0.f};
;         const float glv = (lane < 32) ? P.gl[(b << 8) | (lane << 3) | h] : 0.f;
;         f32x4 ubn[4];
;         const unsigned oU = (unsigned)TR_U + (unsigned)(ct * 256 + lane) * 16u;
;     ...
;         U_LOAD(0);
;         __syncthreads();
; #pragma unroll 1
;         for (int n = 0; n < 32; ++n) {
;             LAS unsigned char* buf = lds + (n & 1) * SB_SZ;
;             const LAS bf16_t* Wl = (const LAS bf16_t*)(buf + SB_W); const LAS bf16_t* Ql = (const LAS bf16_t*)(buf + SB_Q);
;             const LAS bf16_t* Al = (const LAS bf16_t*)(buf + SB_A); const LAS bf16_t* Kl = (const LAS bf16_t*)(buf + SB_K);
;             f32x4 u[4], o[4];
; #pragma unroll
;             for (int mt = 0; mt < 4; ++mt) { u[mt] = ubn[mt]; o[mt] = (f32x4){0.f, 0.f, 0.f, 0.f}; }
;             if (n + 1 < 32) U_LOAD(n + 1);
;     ...
;         { unsigned oO = (unsigned)((q8 * 4) * 1024 + c0 + r) * 4u; asm volatile("" : "+v"(oO));
;           unsigned char* ob = (unsigned char*)(P.obuf + (size_t)(b * SEQ + n * 64) * 1024 + h * 128);
; #pragma unroll
;           for (int mt = 0; mt < 4; ++mt)
; #pragma unroll
;               for (int j = 0; j < 4; ++j) *(float*)(ob + (oO + (unsigned)(mt * 16 + j) * 4096u)) = o[mt][j]; }
.LBB0_528:
	s_or_b64 exec, exec, s[4:5]
	s_lshr_b32 s4, s10, 1
	s_and_b32 s4, s4, 4
	s_and_b32 s5, s11, 3
	s_or_b32 s7, s5, s4
	v_lshlrev_b32_e32 v6, 4, v5
	s_waitcnt vmcnt(11)
	v_lshl_or_b32 v12, s7, 12, v6
	s_or_b32 s6, s6, s8
	v_add_u32_e32 v68, 0x12000, v12
	v_mad_i64_i32 v[6:7], s[4:5], s6, v199, v[116:117]
	v_mov_b32_e32 v69, v153
	v_add_u32_e32 v70, 0x12400, v12
	v_mov_b32_e32 v71, v153
	v_add_u32_e32 v72, 0x12800, v12
	v_mov_b32_e32 v73, v153
	v_add_u32_e32 v74, 0x12c00, v12
	v_mov_b32_e32 v75, v153
	v_lshl_add_u64 v[8:9], v[6:7], 0, v[68:69]
	v_lshl_add_u64 v[10:11], v[6:7], 0, v[72:73]
	v_lshl_add_u64 v[12:13], v[6:7], 0, v[74:75]
	v_lshl_add_u64 v[6:7], v[6:7], 0, v[70:71]
	global_load_dwordx4 v[56:59], v[10:11], off
	global_load_dwordx4 v[52:55], v[12:13], off
	global_load_dwordx4 v[60:63], v[6:7], off
	global_load_dwordx4 v[64:67], v[8:9], off
	s_add_i32 s15, s6, 8
	v_mad_i64_i32 v[44:45], s[16:17], s15, v199, v[116:117]
	v_lshl_add_u64 v[36:37], v[44:45], 0, v[74:75]
	v_lshl_add_u64 v[38:39], v[44:45], 0, v[72:73]
	v_lshl_add_u64 v[46:47], v[44:45], 0, v[70:71]
	v_lshl_add_u64 v[44:45], v[44:45], 0, v[68:69]
	global_load_dwordx4 v[176:179], v[36:37], off
	global_load_dwordx4 v[180:183], v[38:39], off
	global_load_dwordx4 v[184:187], v[46:47], off
	global_load_dwordx4 v[188:191], v[44:45], off
	s_add_i32 s15, s6, 16
	v_mad_i64_i32 v[44:45], s[16:17], s15, v199, v[116:117]
	v_lshl_add_u64 v[36:37], v[44:45], 0, v[74:75]
	v_lshl_add_u64 v[38:39], v[44:45], 0, v[72:73]
	v_lshl_add_u64 v[46:47], v[44:45], 0, v[70:71]
	v_lshl_add_u64 v[44:45], v[44:45], 0, v[68:69]
	global_load_dwordx4 v[200:203], v[36:37], off
	global_load_dwordx4 v[204:207], v[38:39], off
	global_load_dwordx4 v[208:211], v[46:47], off
	global_load_dwordx4 v[212:215], v[44:45], off
	s_add_i32 s15, s6, 24
	v_mad_i64_i32 v[44:45], s[16:17], s15, v199, v[116:117]
	v_lshl_add_u64 v[36:37], v[44:45], 0, v[74:75]
	v_lshl_add_u64 v[38:39], v[44:45], 0, v[72:73]
	v_lshl_add_u64 v[46:47], v[44:45], 0, v[70:71]
	v_lshl_add_u64 v[44:45], v[44:45], 0, v[68:69]
	global_load_dwordx4 v[216:219], v[36:37], off
	global_load_dwordx4 v[220:223], v[38:39], off
	global_load_dwordx4 v[224:227], v[46:47], off
	global_load_dwordx4 v[228:231], v[44:45], off
	s_lshl_b32 s4, s9, 11
	v_lshrrev_b32_e32 v77, 4, v5
	v_or_b32_e32 v6, 48, v5
	v_or_b32_e32 v5, 0x70, v5
	s_ashr_i32 s5, s4, 31
	s_lshl_b32 s7, s7, 4
	v_mul_u32_u24_e32 v81, 0x90, v5
	v_lshlrev_b32_e32 v5, 12, v77
	s_lshl_b64 s[4:5], s[4:5], 12
	s_lshl_b32 s11, s8, 9
	v_or3_b32 v5, v5, v144, s7
	s_or_b32 s4, s4, s11
	v_mul_u32_u24_e32 v7, 0x48, v144
	v_lshlrev_b32_e32 v8, 3, v77
	v_lshlrev_b32_e32 v82, 2, v5
	v_lshlrev_b32_e32 v5, 7, v6
	v_lshl_add_u64 v[2:3], v[2:3], 0, s[4:5]
	v_mul_u32_u24_e32 v78, 0x110, v144
	v_and_b32_e32 v79, 48, v145
	v_mul_u32_u24_e32 v80, 0x110, v6
	s_mov_b32 s10, 0
	v_sub_u32_e32 v83, 0, v5
	v_lshl_add_u64 v[2:3], v[2:3], 0, s[20:21]
	s_mov_b64 s[4:5], 0
	s_mov_b32 s11, 8
	v_lshlrev_b32_e32 v84, 1, v7
	v_lshlrev_b32_e32 v85, 1, v8
	s_mov_b32 s14, 0
	v_mov_b32_e32 v5, v4
	v_mov_b32_e32 v6, v4
	v_mov_b32_e32 v7, v4
	s_waitcnt vmcnt(11)
	v_mov_b32_e32 v28, v4
	v_mov_b32_e32 v29, v4
	v_mov_b32_e32 v30, v4
	v_mov_b32_e32 v31, v4
	s_waitcnt vmcnt(10)
	v_mov_b32_e32 v32, v4
	v_mov_b32_e32 v33, v4
	v_mov_b32_e32 v34, v4
	v_mov_b32_e32 v35, v4
	v_mov_b32_e32 v12, v4
	v_mov_b32_e32 v13, v4
	v_mov_b32_e32 v14, v4
	v_mov_b32_e32 v15, v4
	v_mov_b32_e32 v20, v4
	v_mov_b32_e32 v21, v4
	v_mov_b32_e32 v22, v4
	v_mov_b32_e32 v23, v4
	v_mov_b32_e32 v8, v4
	v_mov_b32_e32 v9, v4
	v_mov_b32_e32 v10, v4
	v_mov_b32_e32 v11, v4
	v_mov_b32_e32 v24, v4
	v_mov_b32_e32 v25, v4
	v_mov_b32_e32 v26, v4
	v_mov_b32_e32 v27, v4
	v_mov_b32_e32 v16, v4
	v_mov_b32_e32 v17, v4
	v_mov_b32_e32 v18, v4
	v_mov_b32_e32 v19, v4
	s_waitcnt lgkmcnt(0)
	s_barrier
	s_waitcnt vmcnt(0)
	v_add_u32_e32 v236, 0x0, v82
	v_add_u32_e32 v237, 0x1000, v82
	v_add_u32_e32 v238, 0x2000, v82
	v_add_u32_e32 v239, 0x3000, v82
	v_add_u32_e32 v240, 0x10000, v82
	v_add_u32_e32 v241, 0x11000, v82
	v_add_u32_e32 v242, 0x12000, v82
	v_add_u32_e32 v243, 0x13000, v82
	v_add_u32_e32 v244, 0x20000, v82
	v_add_u32_e32 v245, 0x21000, v82
	v_add_u32_e32 v246, 0x22000, v82
	v_add_u32_e32 v247, 0x23000, v82
	v_add_u32_e32 v248, 0x30000, v82
	v_add_u32_e32 v249, 0x31000, v82
	v_add_u32_e32 v250, 0x32000, v82
	v_add_u32_e32 v251, 0x33000, v82
	v_readfirstlane_b32 s24, v2
	v_readfirstlane_b32 s25, v3
; #define LAS __attribute__((address_space(3)))
; __device__ __forceinline__ bf16x8 packB(const f32x4& a, const f32x4& b) { u32x4 v = {pk2(a[0], a[1]), pk2(a[2], a[3]), pk2(b[0], b[1]), pk2(b[2], b[3])}; return __builtin_bit_cast(bf16x8, v); }
; #define U_LOAD(nn) do { const unsigned char* tr_ = P.tr + (size_t)((b << 8) | ((nn) << 3) | h) * TR_SZ; \
;             _Pragma("unroll") for (int mt_ = 0; mt_ < 4; ++mt_) ubn[mt_] = *(const f32x4*)(tr_ + (oU + (unsigned)mt_ * 1024u)); } while (0)
; #define SBAR() __builtin_amdgcn_sched_barrier(0)
; #define LD4(d, base, mt, stride) do { _Pragma("unroll") for (int ks = 0; ks < 4; ++ks) d[ks] = frag1((base) + ((mt) * 16 + r) * (stride) + ks * 32 + q8 * 8); } while (0)
; #define MM4(acc, s_) do { _Pragma("unroll") for (int ks = 0; ks < 4; ++ks) acc = __builtin_amdgcn_mfma_f32_16x16x32_bf16(s_[ks], Sb[ks], acc, 0, 0, 0); } while (0)
; __device__ __forceinline__ void scan_bh(LAS unsigned char* lds, const ScanP& P, int b, int h, int half, int tid, int lane, int wave) {
;     ...
;             LAS unsigned char* buf = lds + (n & 1) * SB_SZ;
;             const LAS bf16_t* Wl = (const LAS bf16_t*)(buf + SB_W); const LAS bf16_t* Ql = (const LAS bf16_t*)(buf + SB_Q);
;             const LAS bf16_t* Al = (const LAS bf16_t*)(buf + SB_A); const LAS bf16_t* Kl = (const LAS bf16_t*)(buf + SB_K);
;             f32x4 u[4], o[4];
; #pragma unroll
;             for (int mt = 0; mt < 4; ++mt) { u[mt] = ubn[mt]; o[mt] = (f32x4){0.f, 0.f, 0.f, 0.f}; }
;             if (n + 1 < 32) U_LOAD(n + 1);
;         bf16x8 Sb[4];
; #pragma unroll
;         for (int ks = 0; ks < 4; ++ks) Sb[ks] = packB(S[2 * ks], S[2 * ks + 1]);
;     ...
;         {
;             bf16x8 fA[4], fB[4];
;             LD4(fA, Wl, 0, PS); SBAR(); LD4(fB, Ql, 0, PS); SBAR();
;             MM4(u[0], fA); SBAR(); LD4(fA, Wl, 1, PS); SBAR(); MM4(o[0], fB); SBAR(); LD4(fB, Ql, 1, PS); SBAR();
;             MM4(u[1], fA); SBAR(); LD4(fA, Wl, 2, PS); SBAR(); MM4(o[1], fB); SBAR(); LD4(fB, Ql, 2, PS); SBAR();
;             MM4(u[2], fA); SBAR(); LD4(fA, Wl, 3, PS); SBAR(); MM4(o[2], fB); SBAR(); LD4(fB, Ql, 3, PS); SBAR();
;             MM4(u[3], fA); SBAR(); MM4(o[3], fB); SBAR();
;         }
.Lscan_c0:
	s_add_i32 s15, s11, 24
	s_min_u32 s15, s15, 0xf8
	s_or_b32 s15, s15, s6
	v_mad_i64_i32 v[44:45], s[16:17], s15, v199, v[116:117]
	v_lshl_add_u64 v[36:37], v[44:45], 0, v[74:75]
	v_lshl_add_u64 v[38:39], v[44:45], 0, v[72:73]
	v_lshl_add_u64 v[46:47], v[44:45], 0, v[70:71]
	v_lshl_add_u64 v[44:45], v[44:45], 0, v[68:69]
	global_load_dwordx4 v[160:163], v[36:37], off
	global_load_dwordx4 v[164:167], v[38:39], off
	global_load_dwordx4 v[168:171], v[46:47], off
	global_load_dwordx4 v[172:175], v[44:45], off
	s_waitcnt vmcnt(60)
	s_bitcmp1_b32 s14, 0
	s_cselect_b32 s15, 0xf400, 0
	s_add_i32 s15, s15, 0
	v_add3_u32 v114, s15, v78, v79
	ds_read_b128 v[98:101], v114
	ds_read_b128 v[102:105], v114 offset:64
	ds_read_b128 v[106:109], v114 offset:128
	ds_read_b128 v[110:113], v114 offset:192
	v_cvt_pk_bf16_f32 v86, v4, v5
	v_cvt_pk_bf16_f32 v87, v6, v7
	v_cvt_pk_bf16_f32 v88, v28, v29
	v_cvt_pk_bf16_f32 v89, v30, v31
	v_cvt_pk_bf16_f32 v90, v32, v33
	v_cvt_pk_bf16_f32 v91, v34, v35
	v_cvt_pk_bf16_f32 v92, v12, v13
	v_cvt_pk_bf16_f32 v93, v14, v15
	v_cvt_pk_bf16_f32 v94, v20, v21
	v_cvt_pk_bf16_f32 v95, v22, v23
	v_cvt_pk_bf16_f32 v96, v8, v9
	v_cvt_pk_bf16_f32 v97, v10, v11
	v_cvt_pk_bf16_f32 v118, v24, v25
	v_cvt_pk_bf16_f32 v119, v26, v27
	v_cvt_pk_bf16_f32 v120, v16, v17
	v_cvt_pk_bf16_f32 v121, v18, v19
	ds_read_b128 v[122:125], v114 offset:17408
	ds_read_b128 v[126:129], v114 offset:17472
	ds_read_b128 v[130:133], v114 offset:17536
	ds_read_b128 v[134:137], v114 offset:17600
	s_waitcnt lgkmcnt(7)
	v_mfma_f32_16x16x32_bf16 v[64:67], v[98:101], v[86:89], v[64:67]
	s_waitcnt lgkmcnt(6)
	v_mfma_f32_16x16x32_bf16 v[64:67], v[102:105], v[90:93], v[64:67]
	s_waitcnt lgkmcnt(5)
	v_mfma_f32_16x16x32_bf16 v[64:67], v[106:109], v[94:97], v[64:67]
	s_waitcnt lgkmcnt(4)
	v_mfma_f32_16x16x32_bf16 v[64:67], v[110:113], v[118:121], v[64:67]
	ds_read_b128 v[98:101], v114 offset:4352
	ds_read_b128 v[102:105], v114 offset:4416
	ds_read_b128 v[106:109], v114 offset:4480
	ds_read_b128 v[110:113], v114 offset:4544
	s_waitcnt lgkmcnt(7)
	v_mfma_f32_16x16x32_bf16 v[122:125], v[122:125], v[86:89], 0
	s_waitcnt lgkmcnt(6)
	v_mfma_f32_16x16x32_bf16 v[122:125], v[126:129], v[90:93], v[122:125]
	s_waitcnt lgkmcnt(5)
	v_mfma_f32_16x16x32_bf16 v[122:125], v[130:133], v[94:97], v[122:125]
	s_waitcnt lgkmcnt(4)
	v_mfma_f32_16x16x32_bf16 v[122:125], v[134:137], v[118:121], v[122:125]
	ds_read_b128 v[126:129], v114 offset:21760
	ds_read_b128 v[130:133], v114 offset:21824
	ds_read_b128 v[134:137], v114 offset:21888
	ds_read_b128 v[138:141], v114 offset:21952
	s_waitcnt lgkmcnt(7)
	v_mfma_f32_16x16x32_bf16 v[60:63], v[98:101], v[86:89], v[60:63]
	s_waitcnt lgkmcnt(6)
	v_mfma_f32_16x16x32_bf16 v[60:63], v[102:105], v[90:93], v[60:63]
	s_waitcnt lgkmcnt(5)
	v_mfma_f32_16x16x32_bf16 v[60:63], v[106:109], v[94:97], v[60:63]
	s_waitcnt lgkmcnt(4)
	v_mfma_f32_16x16x32_bf16 v[60:63], v[110:113], v[118:121], v[60:63]
	ds_read_b128 v[98:101], v114 offset:8704
	ds_read_b128 v[102:105], v114 offset:8768
	ds_read_b128 v[106:109], v114 offset:8832
	ds_read_b128 v[110:113], v114 offset:8896
	s_waitcnt lgkmcnt(7)
	v_mfma_f32_16x16x32_bf16 v[126:129], v[126:129], v[86:89], 0
	s_waitcnt lgkmcnt(6)
	v_mfma_f32_16x16x32_bf16 v[126:129], v[130:133], v[90:93], v[126:129]
	s_waitcnt lgkmcnt(5)
	v_mfma_f32_16x16x32_bf16 v[126:129], v[134:137], v[94:97], v[126:129]
	s_waitcnt lgkmcnt(4)
	v_mfma_f32_16x16x32_bf16 v[126:129], v[138:141], v[118:121], v[126:129]
	ds_read_b128 v[130:133], v114 offset:26112
	ds_read_b128 v[134:137], v114 offset:26176
	ds_read_b128 v[138:141], v114 offset:26240
	ds_read_b128 v[146:149], v114 offset:26304
	s_waitcnt lgkmcnt(7)
	v_mfma_f32_16x16x32_bf16 v[56:59], v[98:101], v[86:89], v[56:59]
	s_waitcnt lgkmcnt(6)
	v_mfma_f32_16x16x32_bf16 v[56:59], v[102:105], v[90:93], v[56:59]
	s_waitcnt lgkmcnt(5)
	v_mfma_f32_16x16x32_bf16 v[56:59], v[106:109], v[94:97], v[56:59]
	s_waitcnt lgkmcnt(4)
	v_mfma_f32_16x16x32_bf16 v[56:59], v[110:113], v[118:121], v[56:59]
	v_add_u32_e32 v115, s15, v80
	v_add_u32_e32 v114, v115, v79
	ds_read_b128 v[98:101], v114
	ds_read_b128 v[102:105], v114 offset:64
	ds_read_b128 v[106:109], v114 offset:128
	ds_read_b128 v[110:113], v114 offset:192
	s_waitcnt lgkmcnt(7)
	v_mfma_f32_16x16x32_bf16 v[130:133], v[130:133], v[86:89], 0
	s_waitcnt lgkmcnt(6)
	v_mfma_f32_16x16x32_bf16 v[130:133], v[134:137], v[90:93], v[130:133]
	s_waitcnt lgkmcnt(5)
	v_mfma_f32_16x16x32_bf16 v[130:133], v[138:141], v[94:97], v[130:133]
	s_waitcnt lgkmcnt(4)
	v_mfma_f32_16x16x32_bf16 v[130:133], v[146:149], v[118:121], v[130:133]
	ds_read_b128 v[134:137], v114 offset:17408
	ds_read_b128 v[138:141], v114 offset:17472
	ds_read_b128 v[146:149], v114 offset:17536
	ds_read_b128 v[156:159], v114 offset:17600
	s_waitcnt lgkmcnt(7)
	v_mfma_f32_16x16x32_bf16 v[52:55], v[98:101], v[86:89], v[52:55]
	s_waitcnt lgkmcnt(6)
	v_mfma_f32_16x16x32_bf16 v[52:55], v[102:105], v[90:93], v[52:55]
	s_waitcnt lgkmcnt(5)
	v_mfma_f32_16x16x32_bf16 v[52:55], v[106:109], v[94:97], v[52:55]
	s_waitcnt lgkmcnt(4)
	v_mfma_f32_16x16x32_bf16 v[52:55], v[110:113], v[118:121], v[52:55]
	s_waitcnt lgkmcnt(3)
	v_mfma_f32_16x16x32_bf16 v[86:89], v[134:137], v[86:89], 0
	s_waitcnt lgkmcnt(2)
	v_mfma_f32_16x16x32_bf16 v[86:89], v[138:141], v[90:93], v[86:89]
	s_waitcnt lgkmcnt(1)
	v_mfma_f32_16x16x32_bf16 v[86:89], v[146:149], v[94:97], v[86:89]
	s_waitcnt lgkmcnt(0)
; #define LBAR() do { asm volatile("s_waitcnt lgkmcnt(0)" ::: "memory"); __builtin_amdgcn_s_barrier(); asm volatile("" ::: "memory"); } while (0)
; __device__ __forceinline__ bf16x8 packB(const f32x4& a, const f32x4& b) { u32x4 v = {pk2(a[0], a[1]), pk2(a[2], a[3]), pk2(b[0], b[1]), pk2(b[2], b[3])}; return __builtin_bit_cast(bf16x8, v); }
; #define SBAR() __builtin_amdgcn_sched_barrier(0)
; __device__ __forceinline__ void scan_bh(LAS unsigned char* lds, const ScanP& P, int b, int h, int half, int tid, int lane, int wave) {
;     ...
;         bf16x8 Ub[2];
;         Ub[0] = packB(u[0], u[1]); Ub[1] = packB(u[2], u[3]);
;         const float gl = __shfl(glv, n);
;     ...
;         {
;             bf16x8 aA[6], kA[4], kB[4];
;             aA[0] = frag1(Al + (0 * 16 + r) * TS + q8 * 8); aA[1] = frag1(Al + (1 * 16 + r) * TS + q8 * 8);
;             aA[2] = frag1(Al + (2 * 16 + r) * TS + q8 * 8); aA[3] = frag1(Al + (2 * 16 + r) * TS + 32 + q8 * 8);
;             aA[4] = frag1(Al + (3 * 16 + r) * TS + q8 * 8); aA[5] = frag1(Al + (3 * 16 + r) * TS + 32 + q8 * 8);
;             SBAR(); LDK(kA, 0); SBAR();
;             o[0] = __builtin_amdgcn_mfma_f32_16x16x32_bf16(aA[0], Ub[0], o[0], 0, 0, 0); o[1] = __builtin_amdgcn_mfma_f32_16x16x32_bf16(aA[1], Ub[0], o[1], 0, 0, 0);
;             o[2] = __builtin_amdgcn_mfma_f32_16x16x32_bf16(aA[2], Ub[0], o[2], 0, 0, 0); o[3] = __builtin_amdgcn_mfma_f32_16x16x32_bf16(aA[4], Ub[0], o[3], 0, 0, 0);
;             o[2] = __builtin_amdgcn_mfma_f32_16x16x32_bf16(aA[3], Ub[1], o[2], 0, 0, 0); o[3] = __builtin_amdgcn_mfma_f32_16x16x32_bf16(aA[5], Ub[1], o[3], 0, 0, 0);
;             SBAR(); LDK(kB, 2); SBAR(); MMK(kA, 0); SBAR(); LDK(kA, 4); SBAR(); MMK(kB, 2); SBAR(); LDK(kB, 6); SBAR(); MMK(kA, 4); SBAR(); MMK(kB, 6); SBAR();
;         }
;     ...
;         { unsigned oO = (unsigned)((q8 * 4) * 1024 + c0 + r) * 4u; asm volatile("" : "+v"(oO));
;           unsigned char* ob = (unsigned char*)(P.obuf + (size_t)(b * SEQ + n * 64) * 1024 + h * 128);
; #pragma unroll
;           for (int mt = 0; mt < 4; ++mt)
; #pragma unroll
;               for (int j = 0; j < 4; ++j) *(float*)(ob + (oO + (unsigned)(mt * 16 + j) * 4096u)) = o[mt][j]; }
;             LBAR();
	v_mfma_f32_16x16x32_bf16 v[86:89], v[156:159], v[118:121], v[86:89]
	v_cvt_pk_bf16_f32 v56, v56, v57
	v_cvt_pk_bf16_f32 v57, v58, v59
	v_cvt_pk_bf16_f32 v58, v52, v53
	v_lshlrev_b32_e32 v52, 2, v192
	v_and_b32_e32 v52, 0x100, v52
	v_add_u32_e32 v52, s10, v52
	v_add3_u32 v138, s15, v84, v85
	v_cvt_pk_bf16_f32 v64, v64, v65
	v_cvt_pk_bf16_f32 v65, v66, v67
	v_cvt_pk_bf16_f32 v66, v60, v61
	v_cvt_pk_bf16_f32 v67, v62, v63
	v_cvt_pk_bf16_f32 v59, v54, v55
	ds_bpermute_b32 v114, v52, v76
	ds_read_b128 v[52:55], v138 offset:34816
	ds_read_b128 v[60:63], v138 offset:37120
	ds_read_b128 v[90:93], v138 offset:39424
	ds_read_b128 v[94:97], v138 offset:39488
	v_add3_u32 v115, v115, v83, v85
	ds_read_b128 v[98:101], v115 offset:34816
	ds_read_b128 v[102:105], v115 offset:34880
	ds_read_b128 v[106:109], v138 offset:44032
	ds_read_b128 v[110:113], v138 offset:44096
	ds_read_b128 v[118:121], v138 offset:46336
	ds_read_b128 v[134:137], v138 offset:46400
	s_waitcnt lgkmcnt(9)
	v_mfma_f32_16x16x32_bf16 v[52:55], v[52:55], v[64:67], v[122:125]
	s_waitcnt lgkmcnt(8)
	v_mfma_f32_16x16x32_bf16 v[60:63], v[60:63], v[64:67], v[126:129]
	s_waitcnt lgkmcnt(7)
	v_mfma_f32_16x16x32_bf16 v[90:93], v[90:93], v[64:67], v[130:133]
	s_waitcnt lgkmcnt(5)
	v_mfma_f32_16x16x32_bf16 v[86:89], v[98:101], v[64:67], v[86:89]
	v_mfma_f32_16x16x32_bf16 v[90:93], v[94:97], v[56:59], v[90:93]
	s_waitcnt lgkmcnt(4)
	v_mfma_f32_16x16x32_bf16 v[86:89], v[102:105], v[56:59], v[86:89]
	ds_read_b128 v[94:97], v138 offset:48640
	ds_read_b128 v[98:101], v138 offset:48704
	ds_read_b128 v[102:105], v115 offset:44032
	ds_read_b128 v[122:125], v115 offset:44096
	v_pk_mul_f32 v[6:7], v[6:7], v[114:115] op_sel_hi:[1,0]
	v_pk_mul_f32 v[4:5], v[4:5], v[114:115] op_sel_hi:[1,0]
	v_pk_mul_f32 v[30:31], v[30:31], v[114:115] op_sel_hi:[1,0]
	v_pk_mul_f32 v[28:29], v[28:29], v[114:115] op_sel_hi:[1,0]
	s_waitcnt lgkmcnt(7)
	v_mfma_f32_16x16x32_bf16 v[4:7], v[106:109], v[64:67], v[4:7]
	s_waitcnt lgkmcnt(5)
	v_mfma_f32_16x16x32_bf16 v[28:31], v[118:121], v[64:67], v[28:31]
	v_mfma_f32_16x16x32_bf16 v[4:7], v[110:113], v[56:59], v[4:7]
	s_waitcnt lgkmcnt(4)
	v_mfma_f32_16x16x32_bf16 v[28:31], v[134:137], v[56:59], v[28:31]
	ds_read_b128 v[106:109], v138 offset:53248
	ds_read_b128 v[110:113], v138 offset:53312
	ds_read_b128 v[118:121], v138 offset:55552
	ds_read_b128 v[126:129], v138 offset:55616
	v_pk_mul_f32 v[34:35], v[34:35], v[114:115] op_sel_hi:[1,0]
	v_pk_mul_f32 v[32:33], v[32:33], v[114:115] op_sel_hi:[1,0]
	v_pk_mul_f32 v[14:15], v[14:15], v[114:115] op_sel_hi:[1,0]
	v_pk_mul_f32 v[12:13], v[12:13], v[114:115] op_sel_hi:[1,0]
	s_waitcnt lgkmcnt(7)
	v_mfma_f32_16x16x32_bf16 v[32:35], v[94:97], v[64:67], v[32:35]
	s_waitcnt lgkmcnt(5)
	v_mfma_f32_16x16x32_bf16 v[12:15], v[102:105], v[64:67], v[12:15]
	v_mfma_f32_16x16x32_bf16 v[32:35], v[98:101], v[56:59], v[32:35]
	s_waitcnt lgkmcnt(4)
	v_mfma_f32_16x16x32_bf16 v[12:15], v[122:125], v[56:59], v[12:15]
	v_add3_u32 v115, s15, v81, v85
	ds_read_b128 v[94:97], v138 offset:57856
	ds_read_b128 v[98:101], v138 offset:57920
	ds_read_b128 v[102:105], v115 offset:44032
	ds_read_b128 v[122:125], v115 offset:44096
	v_pk_mul_f32 v[22:23], v[22:23], v[114:115] op_sel_hi:[1,0]
	v_pk_mul_f32 v[20:21], v[20:21], v[114:115] op_sel_hi:[1,0]
	v_pk_mul_f32 v[10:11], v[10:11], v[114:115] op_sel_hi:[1,0]
	v_pk_mul_f32 v[8:9], v[8:9], v[114:115] op_sel_hi:[1,0]
	s_waitcnt lgkmcnt(7)
	v_mfma_f32_16x16x32_bf16 v[20:23], v[106:109], v[64:67], v[20:23]
	s_waitcnt lgkmcnt(5)
	v_mfma_f32_16x16x32_bf16 v[8:11], v[118:121], v[64:67], v[8:11]
	v_mfma_f32_16x16x32_bf16 v[20:23], v[110:113], v[56:59], v[20:23]
	s_waitcnt lgkmcnt(4)
	v_mfma_f32_16x16x32_bf16 v[8:11], v[126:129], v[56:59], v[8:11]
	v_mul_f32_e64 v26, v26, v114
	v_mul_f32_e64 v27, v27, v114
	v_pk_mul_f32 v[24:25], v[24:25], v[114:115] op_sel_hi:[1,0]
	v_pk_mul_f32 v[18:19], v[18:19], v[114:115] op_sel_hi:[1,0]
	v_pk_mul_f32 v[16:17], v[16:17], v[114:115] op_sel_hi:[1,0]
	s_waitcnt lgkmcnt(3)
	v_mfma_f32_16x16x32_bf16 v[24:27], v[94:97], v[64:67], v[24:27]
	s_waitcnt lgkmcnt(1)
	v_mfma_f32_16x16x32_bf16 v[16:19], v[102:105], v[64:67], v[16:19]
	v_mfma_f32_16x16x32_bf16 v[24:27], v[98:101], v[56:59], v[24:27]
	s_waitcnt lgkmcnt(0)
	v_mfma_f32_16x16x32_bf16 v[16:19], v[122:125], v[56:59], v[16:19]
	s_add_u32 s22, s24, s4
	s_addc_u32 s23, s25, s5
	v_mov_b64_e32 v[66:67], v[190:191]
	global_store_dword v236, v52, s[22:23]
	global_store_dword v237, v53, s[22:23]
	global_store_dword v238, v54, s[22:23]
	global_store_dword v239, v55, s[22:23]
	global_store_dword v240, v60, s[22:23]
	global_store_dword v241, v61, s[22:23]
	global_store_dword v242, v62, s[22:23]
	global_store_dword v243, v63, s[22:23]
	global_store_dword v244, v90, s[22:23]
	global_store_dword v245, v91, s[22:23]
	global_store_dword v246, v92, s[22:23]
	global_store_dword v247, v93, s[22:23]
	global_store_dword v248, v86, s[22:23]
	global_store_dword v249, v87, s[22:23]
	global_store_dword v250, v88, s[22:23]
	global_store_dword v251, v89, s[22:23]
	s_waitcnt lgkmcnt(0)
	s_barrier
	s_add_u32 s4, s4, 0x40000
	s_addc_u32 s5, s5, 0
	s_add_i32 s10, s10, 4
	s_add_i32 s11, s11, 8
	s_add_i32 s14, s14, 1
	v_mov_b64_e32 v[54:55], v[178:179]
	v_mov_b64_e32 v[58:59], v[182:183]
	v_mov_b64_e32 v[62:63], v[186:187]
	s_cmp_eq_u32 s4, 0x800000
	v_mov_b64_e32 v[52:53], v[176:177]
	v_mov_b64_e32 v[56:57], v[180:181]
	v_mov_b64_e32 v[60:61], v[184:185]
	v_mov_b64_e32 v[64:65], v[188:189]
; #define LAS __attribute__((address_space(3)))
; __device__ __forceinline__ bf16x8 packB(const f32x4& a, const f32x4& b) { u32x4 v = {pk2(a[0], a[1]), pk2(a[2], a[3]), pk2(b[0], b[1]), pk2(b[2], b[3])}; return __builtin_bit_cast(bf16x8, v); }
; #define U_LOAD(nn) do { const unsigned char* tr_ = P.tr + (size_t)((b << 8) | ((nn) << 3) | h) * TR_SZ; \
;             _Pragma("unroll") for (int mt_ = 0; mt_ < 4; ++mt_) ubn[mt_] = *(const f32x4*)(tr_ + (oU + (unsigned)mt_ * 1024u)); } while (0)
; #define SBAR() __builtin_amdgcn_sched_barrier(0)
; #define LD4(d, base, mt, stride) do { _Pragma("unroll") for (int ks = 0; ks < 4; ++ks) d[ks] = frag1((base) + ((mt) * 16 + r) * (stride) + ks * 32 + q8 * 8); } while (0)
; #define MM4(acc, s_) do { _Pragma("unroll") for (int ks = 0; ks < 4; ++ks) acc = __builtin_amdgcn_mfma_f32_16x16x32_bf16(s_[ks], Sb[ks], acc, 0, 0, 0); } while (0)
; __device__ __forceinline__ void scan_bh(LAS unsigned char* lds, const ScanP& P, int b, int h, int half, int tid, int lane, int wave) {
;     ...
;             LAS unsigned char* buf = lds + (n & 1) * SB_SZ;
;             const LAS bf16_t* Wl = (const LAS bf16_t*)(buf + SB_W); const LAS bf16_t* Ql = (const LAS bf16_t*)(buf + SB_Q);
;             const LAS bf16_t* Al = (const LAS bf16_t*)(buf + SB_A); const LAS bf16_t* Kl = (const LAS bf16_t*)(buf + SB_K);
;             f32x4 u[4], o[4];
; #pragma unroll
;             for (int mt = 0; mt < 4; ++mt) { u[mt] = ubn[mt]; o[mt] = (f32x4){0.f, 0.f, 0.f, 0.f}; }
;             if (n + 1 < 32) U_LOAD(n + 1);
;         bf16x8 Sb[4];
; #pragma unroll
;         for (int ks = 0; ks < 4; ++ks) Sb[ks] = packB(S[2 * ks], S[2 * ks + 1]);
;     ...
;         {
;             bf16x8 fA[4], fB[4];
;             LD4(fA, Wl, 0, PS); SBAR(); LD4(fB, Ql, 0, PS); SBAR();
;             MM4(u[0], fA); SBAR(); LD4(fA, Wl, 1, PS); SBAR(); MM4(o[0], fB); SBAR(); LD4(fB, Ql, 1, PS); SBAR();
;             MM4(u[1], fA); SBAR(); LD4(fA, Wl, 2, PS); SBAR(); MM4(o[1], fB); SBAR(); LD4(fB, Ql, 2, PS); SBAR();
;             MM4(u[2], fA); SBAR(); LD4(fA, Wl, 3, PS); SBAR(); MM4(o[2], fB); SBAR(); LD4(fB, Ql, 3, PS); SBAR();
;             MM4(u[3], fA); SBAR(); MM4(o[3], fB); SBAR();
;         }
.Lscan_c1:
	s_add_i32 s15, s11, 24
	s_min_u32 s15, s15, 0xf8
	s_or_b32 s15, s15, s6
	v_mad_i64_i32 v[44:45], s[16:17], s15, v199, v[116:117]
	v_lshl_add_u64 v[36:37], v[44:45], 0, v[74:75]
	v_lshl_add_u64 v[38:39], v[44:45], 0, v[72:73]
	v_lshl_add_u64 v[46:47], v[44:45], 0, v[70:71]
	v_lshl_add_u64 v[44:45], v[44:45], 0, v[68:69]
	global_load_dwordx4 v[176:179], v[36:37], off
	global_load_dwordx4 v[180:183], v[38:39], off
	global_load_dwordx4 v[184:187], v[46:47], off
	global_load_dwordx4 v[188:191], v[44:45], off
	s_waitcnt vmcnt(60)
	s_bitcmp1_b32 s14, 0
	s_cselect_b32 s15, 0xf400, 0
	s_add_i32 s15, s15, 0
	v_add3_u32 v114, s15, v78, v79
	ds_read_b128 v[98:101], v114
	ds_read_b128 v[102:105], v114 offset:64
	ds_read_b128 v[106:109], v114 offset:128
	ds_read_b128 v[110:113], v114 offset:192
	v_cvt_pk_bf16_f32 v86, v4, v5
	v_cvt_pk_bf16_f32 v87, v6, v7
	v_cvt_pk_bf16_f32 v88, v28, v29
	v_cvt_pk_bf16_f32 v89, v30, v31
	v_cvt_pk_bf16_f32 v90, v32, v33
	v_cvt_pk_bf16_f32 v91, v34, v35
	v_cvt_pk_bf16_f32 v92, v12, v13
	v_cvt_pk_bf16_f32 v93, v14, v15
	v_cvt_pk_bf16_f32 v94, v20, v21
	v_cvt_pk_bf16_f32 v95, v22, v23
	v_cvt_pk_bf16_f32 v96, v8, v9
	v_cvt_pk_bf16_f32 v97, v10, v11
	v_cvt_pk_bf16_f32 v118, v24, v25
	v_cvt_pk_bf16_f32 v119, v26, v27
	v_cvt_pk_bf16_f32 v120, v16, v17
	v_cvt_pk_bf16_f32 v121, v18, v19
	ds_read_b128 v[122:125], v114 offset:17408
	ds_read_b128 v[126:129], v114 offset:17472
	ds_read_b128 v[130:133], v114 offset:17536
	ds_read_b128 v[134:137], v114 offset:17600
	s_waitcnt lgkmcnt(7)
	v_mfma_f32_16x16x32_bf16 v[64:67], v[98:101], v[86:89], v[64:67]
	s_waitcnt lgkmcnt(6)
	v_mfma_f32_16x16x32_bf16 v[64:67], v[102:105], v[90:93], v[64:67]
	s_waitcnt lgkmcnt(5)
	v_mfma_f32_16x16x32_bf16 v[64:67], v[106:109], v[94:97], v[64:67]
	s_waitcnt lgkmcnt(4)
	v_mfma_f32_16x16x32_bf16 v[64:67], v[110:113], v[118:121], v[64:67]
	ds_read_b128 v[98:101], v114 offset:4352
	ds_read_b128 v[102:105], v114 offset:4416
	ds_read_b128 v[106:109], v114 offset:4480
	ds_read_b128 v[110:113], v114 offset:4544
	s_waitcnt lgkmcnt(7)
	v_mfma_f32_16x16x32_bf16 v[122:125], v[122:125], v[86:89], 0
	s_waitcnt lgkmcnt(6)
	v_mfma_f32_16x16x32_bf16 v[122:125], v[126:129], v[90:93], v[122:125]
	s_waitcnt lgkmcnt(5)
	v_mfma_f32_16x16x32_bf16 v[122:125], v[130:133], v[94:97], v[122:125]
	s_waitcnt lgkmcnt(4)
	v_mfma_f32_16x16x32_bf16 v[122:125], v[134:137], v[118:121], v[122:125]
	ds_read_b128 v[126:129], v114 offset:21760
	ds_read_b128 v[130:133], v114 offset:21824
	ds_read_b128 v[134:137], v114 offset:21888
	ds_read_b128 v[138:141], v114 offset:21952
	s_waitcnt lgkmcnt(7)
	v_mfma_f32_16x16x32_bf16 v[60:63], v[98:101], v[86:89], v[60:63]
	s_waitcnt lgkmcnt(6)
	v_mfma_f32_16x16x32_bf16 v[60:63], v[102:105], v[90:93], v[60:63]
	s_waitcnt lgkmcnt(5)
	v_mfma_f32_16x16x32_bf16 v[60:63], v[106:109], v[94:97], v[60:63]
	s_waitcnt lgkmcnt(4)
	v_mfma_f32_16x16x32_bf16 v[60:63], v[110:113], v[118:121], v[60:63]
	ds_read_b128 v[98:101], v114 offset:8704
	ds_read_b128 v[102:105], v114 offset:8768
	ds_read_b128 v[106:109], v114 offset:8832
	ds_read_b128 v[110:113], v114 offset:8896
	s_waitcnt lgkmcnt(7)
	v_mfma_f32_16x16x32_bf16 v[126:129], v[126:129], v[86:89], 0
	s_waitcnt lgkmcnt(6)
	v_mfma_f32_16x16x32_bf16 v[126:129], v[130:133], v[90:93], v[126:129]
	s_waitcnt lgkmcnt(5)
	v_mfma_f32_16x16x32_bf16 v[126:129], v[134:137], v[94:97], v[126:129]
	s_waitcnt lgkmcnt(4)
	v_mfma_f32_16x16x32_bf16 v[126:129], v[138:141], v[118:121], v[126:129]
	ds_read_b128 v[130:133], v114 offset:26112
	ds_read_b128 v[134:137], v114 offset:26176
	ds_read_b128 v[138:141], v114 offset:26240
	ds_read_b128 v[146:149], v114 offset:26304
	s_waitcnt lgkmcnt(7)
	v_mfma_f32_16x16x32_bf16 v[56:59], v[98:101], v[86:89], v[56:59]
	s_waitcnt lgkmcnt(6)
	v_mfma_f32_16x16x32_bf16 v[56:59], v[102:105], v[90:93], v[56:59]
	s_waitcnt lgkmcnt(5)
	v_mfma_f32_16x16x32_bf16 v[56:59], v[106:109], v[94:97], v[56:59]
	s_waitcnt lgkmcnt(4)
	v_mfma_f32_16x16x32_bf16 v[56:59], v[110:113], v[118:121], v[56:59]
	v_add_u32_e32 v115, s15, v80
	v_add_u32_e32 v114, v115, v79
	ds_read_b128 v[98:101], v114
	ds_read_b128 v[102:105], v114 offset:64
	ds_read_b128 v[106:109], v114 offset:128
	ds_read_b128 v[110:113], v114 offset:192
	s_waitcnt lgkmcnt(7)
	v_mfma_f32_16x16x32_bf16 v[130:133], v[130:133], v[86:89], 0
	s_waitcnt lgkmcnt(6)
	v_mfma_f32_16x16x32_bf16 v[130:133], v[134:137], v[90:93], v[130:133]
	s_waitcnt lgkmcnt(5)
	v_mfma_f32_16x16x32_bf16 v[130:133], v[138:141], v[94:97], v[130:133]
	s_waitcnt lgkmcnt(4)
	v_mfma_f32_16x16x32_bf16 v[130:133], v[146:149], v[118:121], v[130:133]
	ds_read_b128 v[134:137], v114 offset:17408
	ds_read_b128 v[138:141], v114 offset:17472
	ds_read_b128 v[146:149], v114 offset:17536
	ds_read_b128 v[156:159], v114 offset:17600
	s_waitcnt lgkmcnt(7)
	v_mfma_f32_16x16x32_bf16 v[52:55], v[98:101], v[86:89], v[52:55]
	s_waitcnt lgkmcnt(6)
	v_mfma_f32_16x16x32_bf16 v[52:55], v[102:105], v[90:93], v[52:55]
	s_waitcnt lgkmcnt(5)
	v_mfma_f32_16x16x32_bf16 v[52:55], v[106:109], v[94:97], v[52:55]
	s_waitcnt lgkmcnt(4)
	v_mfma_f32_16x16x32_bf16 v[52:55], v[110:113], v[118:121], v[52:55]
	s_waitcnt lgkmcnt(3)
	v_mfma_f32_16x16x32_bf16 v[86:89], v[134:137], v[86:89], 0
	s_waitcnt lgkmcnt(2)
	v_mfma_f32_16x16x32_bf16 v[86:89], v[138:141], v[90:93], v[86:89]
	s_waitcnt lgkmcnt(1)
	v_mfma_f32_16x16x32_bf16 v[86:89], v[146:149], v[94:97], v[86:89]
	s_waitcnt lgkmcnt(0)
; #define LBAR() do { asm volatile("s_waitcnt lgkmcnt(0)" ::: "memory"); __builtin_amdgcn_s_barrier(); asm volatile("" ::: "memory"); } while (0)
; __device__ __forceinline__ bf16x8 packB(const f32x4& a, const f32x4& b) { u32x4 v = {pk2(a[0], a[1]), pk2(a[2], a[3]), pk2(b[0], b[1]), pk2(b[2], b[3])}; return __builtin_bit_cast(bf16x8, v); }
; #define SBAR() __builtin_amdgcn_sched_barrier(0)
; __device__ __forceinline__ void scan_bh(LAS unsigned char* lds, const ScanP& P, int b, int h, int half, int tid, int lane, int wave) {
;     ...
;         bf16x8 Ub[2];
;         Ub[0] = packB(u[0], u[1]); Ub[1] = packB(u[2], u[3]);
;         const float gl = __shfl(glv, n);
;     ...
;         {
;             bf16x8 aA[6], kA[4], kB[4];
;             aA[0] = frag1(Al + (0 * 16 + r) * TS + q8 * 8); aA[1] = frag1(Al + (1 * 16 + r) * TS + q8 * 8);
;             aA[2] = frag1(Al + (2 * 16 + r) * TS + q8 * 8); aA[3] = frag1(Al + (2 * 16 + r) * TS + 32 + q8 * 8);
;             aA[4] = frag1(Al + (3 * 16 + r) * TS + q8 * 8); aA[5] = frag1(Al + (3 * 16 + r) * TS + 32 + q8 * 8);
;             SBAR(); LDK(kA, 0); SBAR();
;             o[0] = __builtin_amdgcn_mfma_f32_16x16x32_bf16(aA[0], Ub[0], o[0], 0, 0, 0); o[1] = __builtin_amdgcn_mfma_f32_16x16x32_bf16(aA[1], Ub[0], o[1], 0, 0, 0);
;             o[2] = __builtin_amdgcn_mfma_f32_16x16x32_bf16(aA[2], Ub[0], o[2], 0, 0, 0); o[3] = __builtin_amdgcn_mfma_f32_16x16x32_bf16(aA[4], Ub[0], o[3], 0, 0, 0);
;             o[2] = __builtin_amdgcn_mfma_f32_16x16x32_bf16(aA[3], Ub[1], o[2], 0, 0, 0); o[3] = __builtin_amdgcn_mfma_f32_16x16x32_bf16(aA[5], Ub[1], o[3], 0, 0, 0);
;             SBAR(); LDK(kB, 2); SBAR(); MMK(kA, 0); SBAR(); LDK(kA, 4); SBAR(); MMK(kB, 2); SBAR(); LDK(kB, 6); SBAR(); MMK(kA, 4); SBAR(); MMK(kB, 6); SBAR();
;         }
;     ...
;         { unsigned oO = (unsigned)((q8 * 4) * 1024 + c0 + r) * 4u; asm volatile("" : "+v"(oO));
;           unsigned char* ob = (unsigned char*)(P.obuf + (size_t)(b * SEQ + n * 64) * 1024 + h * 128);
; #pragma unroll
;           for (int mt = 0; mt < 4; ++mt)
; #pragma unroll
;               for (int j = 0; j < 4; ++j) *(float*)(ob + (oO + (unsigned)(mt * 16 + j) * 4096u)) = o[mt][j]; }
;             LBAR();
	v_mfma_f32_16x16x32_bf16 v[86:89], v[156:159], v[118:121], v[86:89]
	v_cvt_pk_bf16_f32 v56, v56, v57
	v_cvt_pk_bf16_f32 v57, v58, v59
	v_cvt_pk_bf16_f32 v58, v52, v53
	v_lshlrev_b32_e32 v52, 2, v192
	v_and_b32_e32 v52, 0x100, v52
	v_add_u32_e32 v52, s10, v52
	v_add3_u32 v138, s15, v84, v85
	v_cvt_pk_bf16_f32 v64, v64, v65
	v_cvt_pk_bf16_f32 v65, v66, v67
	v_cvt_pk_bf16_f32 v66, v60, v61
	v_cvt_pk_bf16_f32 v67, v62, v63
	v_cvt_pk_bf16_f32 v59, v54, v55
	ds_bpermute_b32 v114, v52, v76
	ds_read_b128 v[52:55], v138 offset:34816
	ds_read_b128 v[60:63], v138 offset:37120
	ds_read_b128 v[90:93], v138 offset:39424
	ds_read_b128 v[94:97], v138 offset:39488
	v_add3_u32 v115, v115, v83, v85
	ds_read_b128 v[98:101], v115 offset:34816
	ds_read_b128 v[102:105], v115 offset:34880
	ds_read_b128 v[106:109], v138 offset:44032
	ds_read_b128 v[110:113], v138 offset:44096
	ds_read_b128 v[118:121], v138 offset:46336
	ds_read_b128 v[134:137], v138 offset:46400
	s_waitcnt lgkmcnt(9)
	v_mfma_f32_16x16x32_bf16 v[52:55], v[52:55], v[64:67], v[122:125]
	s_waitcnt lgkmcnt(8)
	v_mfma_f32_16x16x32_bf16 v[60:63], v[60:63], v[64:67], v[126:129]
	s_waitcnt lgkmcnt(7)
	v_mfma_f32_16x16x32_bf16 v[90:93], v[90:93], v[64:67], v[130:133]
	s_waitcnt lgkmcnt(5)
	v_mfma_f32_16x16x32_bf16 v[86:89], v[98:101], v[64:67], v[86:89]
	v_mfma_f32_16x16x32_bf16 v[90:93], v[94:97], v[56:59], v[90:93]
	s_waitcnt lgkmcnt(4)
	v_mfma_f32_16x16x32_bf16 v[86:89], v[102:105], v[56:59], v[86:89]
	ds_read_b128 v[94:97], v138 offset:48640
	ds_read_b128 v[98:101], v138 offset:48704
	ds_read_b128 v[102:105], v115 offset:44032
	ds_read_b128 v[122:125], v115 offset:44096
	v_pk_mul_f32 v[6:7], v[6:7], v[114:115] op_sel_hi:[1,0]
	v_pk_mul_f32 v[4:5], v[4:5], v[114:115] op_sel_hi:[1,0]
	v_pk_mul_f32 v[30:31], v[30:31], v[114:115] op_sel_hi:[1,0]
	v_pk_mul_f32 v[28:29], v[28:29], v[114:115] op_sel_hi:[1,0]
	s_waitcnt lgkmcnt(7)
	v_mfma_f32_16x16x32_bf16 v[4:7], v[106:109], v[64:67], v[4:7]
	s_waitcnt lgkmcnt(5)
	v_mfma_f32_16x16x32_bf16 v[28:31], v[118:121], v[64:67], v[28:31]
	v_mfma_f32_16x16x32_bf16 v[4:7], v[110:113], v[56:59], v[4:7]
	s_waitcnt lgkmcnt(4)
	v_mfma_f32_16x16x32_bf16 v[28:31], v[134:137], v[56:59], v[28:31]
	ds_read_b128 v[106:109], v138 offset:53248
	ds_read_b128 v[110:113], v138 offset:53312
	ds_read_b128 v[118:121], v138 offset:55552
	ds_read_b128 v[126:129], v138 offset:55616
	v_pk_mul_f32 v[34:35], v[34:35], v[114:115] op_sel_hi:[1,0]
	v_pk_mul_f32 v[32:33], v[32:33], v[114:115] op_sel_hi:[1,0]
	v_pk_mul_f32 v[14:15], v[14:15], v[114:115] op_sel_hi:[1,0]
	v_pk_mul_f32 v[12:13], v[12:13], v[114:115] op_sel_hi:[1,0]
	s_waitcnt lgkmcnt(7)
	v_mfma_f32_16x16x32_bf16 v[32:35], v[94:97], v[64:67], v[32:35]
	s_waitcnt lgkmcnt(5)
	v_mfma_f32_16x16x32_bf16 v[12:15], v[102:105], v[64:67], v[12:15]
	v_mfma_f32_16x16x32_bf16 v[32:35], v[98:101], v[56:59], v[32:35]
	s_waitcnt lgkmcnt(4)
	v_mfma_f32_16x16x32_bf16 v[12:15], v[122:125], v[56:59], v[12:15]
	v_add3_u32 v115, s15, v81, v85
	ds_read_b128 v[94:97], v138 offset:57856
	ds_read_b128 v[98:101], v138 offset:57920
	ds_read_b128 v[102:105], v115 offset:44032
	ds_read_b128 v[122:125], v115 offset:44096
	v_pk_mul_f32 v[22:23], v[22:23], v[114:115] op_sel_hi:[1,0]
	v_pk_mul_f32 v[20:21], v[20:21], v[114:115] op_sel_hi:[1,0]
	v_pk_mul_f32 v[10:11], v[10:11], v[114:115] op_sel_hi:[1,0]
	v_pk_mul_f32 v[8:9], v[8:9], v[114:115] op_sel_hi:[1,0]
	s_waitcnt lgkmcnt(7)
	v_mfma_f32_16x16x32_bf16 v[20:23], v[106:109], v[64:67], v[20:23]
	s_waitcnt lgkmcnt(5)
	v_mfma_f32_16x16x32_bf16 v[8:11], v[118:121], v[64:67], v[8:11]
	v_mfma_f32_16x16x32_bf16 v[20:23], v[110:113], v[56:59], v[20:23]
	s_waitcnt lgkmcnt(4)
	v_mfma_f32_16x16x32_bf16 v[8:11], v[126:129], v[56:59], v[8:11]
	v_mul_f32_e64 v26, v26, v114
	v_mul_f32_e64 v27, v27, v114
	v_pk_mul_f32 v[24:25], v[24:25], v[114:115] op_sel_hi:[1,0]
	v_pk_mul_f32 v[18:19], v[18:19], v[114:115] op_sel_hi:[1,0]
	v_pk_mul_f32 v[16:17], v[16:17], v[114:115] op_sel_hi:[1,0]
	s_waitcnt lgkmcnt(3)
	v_mfma_f32_16x16x32_bf16 v[24:27], v[94:97], v[64:67], v[24:27]
	s_waitcnt lgkmcnt(1)
	v_mfma_f32_16x16x32_bf16 v[16:19], v[102:105], v[64:67], v[16:19]
	v_mfma_f32_16x16x32_bf16 v[24:27], v[98:101], v[56:59], v[24:27]
	s_waitcnt lgkmcnt(0)
	v_mfma_f32_16x16x32_bf16 v[16:19], v[122:125], v[56:59], v[16:19]
	s_add_u32 s22, s24, s4
	s_addc_u32 s23, s25, s5
	v_mov_b64_e32 v[66:67], v[214:215]
	global_store_dword v236, v52, s[22:23]
	global_store_dword v237, v53, s[22:23]
	global_store_dword v238, v54, s[22:23]
	global_store_dword v239, v55, s[22:23]
	global_store_dword v240, v60, s[22:23]
	global_store_dword v241, v61, s[22:23]
	global_store_dword v242, v62, s[22:23]
	global_store_dword v243, v63, s[22:23]
	global_store_dword v244, v90, s[22:23]
	global_store_dword v245, v91, s[22:23]
	global_store_dword v246, v92, s[22:23]
	global_store_dword v247, v93, s[22:23]
	global_store_dword v248, v86, s[22:23]
	global_store_dword v249, v87, s[22:23]
	global_store_dword v250, v88, s[22:23]
	global_store_dword v251, v89, s[22:23]
	s_waitcnt lgkmcnt(0)
	s_barrier
	s_add_u32 s4, s4, 0x40000
	s_addc_u32 s5, s5, 0
	s_add_i32 s10, s10, 4
	s_add_i32 s11, s11, 8
	s_add_i32 s14, s14, 1
	v_mov_b64_e32 v[54:55], v[202:203]
	v_mov_b64_e32 v[58:59], v[206:207]
	v_mov_b64_e32 v[62:63], v[210:211]
	s_cmp_eq_u32 s4, 0x800000
	v_mov_b64_e32 v[52:53], v[200:201]
	v_mov_b64_e32 v[56:57], v[204:205]
	v_mov_b64_e32 v[60:61], v[208:209]
	v_mov_b64_e32 v[64:65], v[212:213]
; #define LAS __attribute__((address_space(3)))
; __device__ __forceinline__ bf16x8 packB(const f32x4& a, const f32x4& b) { u32x4 v = {pk2(a[0], a[1]), pk2(a[2], a[3]), pk2(b[0], b[1]), pk2(b[2], b[3])}; return __builtin_bit_cast(bf16x8, v); }
; #define U_LOAD(nn) do { const unsigned char* tr_ = P.tr + (size_t)((b << 8) | ((nn) << 3) | h) * TR_SZ; \
;             _Pragma("unroll") for (int mt_ = 0; mt_ < 4; ++mt_) ubn[mt_] = *(const f32x4*)(tr_ + (oU + (unsigned)mt_ * 1024u)); } while (0)
; #define SBAR() __builtin_amdgcn_sched_barrier(0)
; #define LD4(d, base, mt, stride) do { _Pragma("unroll") for (int ks = 0; ks < 4; ++ks) d[ks] = frag1((base) + ((mt) * 16 + r) * (stride) + ks * 32 + q8 * 8); } while (0)
; #define MM4(acc, s_) do { _Pragma("unroll") for (int ks = 0; ks < 4; ++ks) acc = __builtin_amdgcn_mfma_f32_16x16x32_bf16(s_[ks], Sb[ks], acc, 0, 0, 0); } while (0)
; __device__ __forceinline__ void scan_bh(LAS unsigned char* lds, const ScanP& P, int b, int h, int half, int tid, int lane, int wave) {
;     ...
;             LAS unsigned char* buf = lds + (n & 1) * SB_SZ;
;             const LAS bf16_t* Wl = (const LAS bf16_t*)(buf + SB_W); const LAS bf16_t* Ql = (const LAS bf16_t*)(buf + SB_Q);
;             const LAS bf16_t* Al = (const LAS bf16_t*)(buf + SB_A); const LAS bf16_t* Kl = (const LAS bf16_t*)(buf + SB_K);
;             f32x4 u[4], o[4];
; #pragma unroll
;             for (int mt = 0; mt < 4; ++mt) { u[mt] = ubn[mt]; o[mt] = (f32x4){0.f, 0.f, 0.f, 0.f}; }
;             if (n + 1 < 32) U_LOAD(n + 1);
;         bf16x8 Sb[4];
; #pragma unroll
;         for (int ks = 0; ks < 4; ++ks) Sb[ks] = packB(S[2 * ks], S[2 * ks + 1]);
;     ...
;         {
;             bf16x8 fA[4], fB[4];
;             LD4(fA, Wl, 0, PS); SBAR(); LD4(fB, Ql, 0, PS); SBAR();
;             MM4(u[0], fA); SBAR(); LD4(fA, Wl, 1, PS); SBAR(); MM4(o[0], fB); SBAR(); LD4(fB, Ql, 1, PS); SBAR();
;             MM4(u[1], fA); SBAR(); LD4(fA, Wl, 2, PS); SBAR(); MM4(o[1], fB); SBAR(); LD4(fB, Ql, 2, PS); SBAR();
;             MM4(u[2], fA); SBAR(); LD4(fA, Wl, 3, PS); SBAR(); MM4(o[2], fB); SBAR(); LD4(fB, Ql, 3, PS); SBAR();
;             MM4(u[3], fA); SBAR(); MM4(o[3], fB); SBAR();
;         }
.Lscan_c2:
	s_add_i32 s15, s11, 24
	s_min_u32 s15, s15, 0xf8
	s_or_b32 s15, s15, s6
	v_mad_i64_i32 v[44:45], s[16:17], s15, v199, v[116:117]
	v_lshl_add_u64 v[36:37], v[44:45], 0, v[74:75]
	v_lshl_add_u64 v[38:39], v[44:45], 0, v[72:73]
	v_lshl_add_u64 v[46:47], v[44:45], 0, v[70:71]
	v_lshl_add_u64 v[44:45], v[44:45], 0, v[68:69]
	global_load_dwordx4 v[200:203], v[36:37], off
	global_load_dwordx4 v[204:207], v[38:39], off
	global_load_dwordx4 v[208:211], v[46:47], off
	global_load_dwordx4 v[212:215], v[44:45], off
	s_waitcnt vmcnt(60)
	s_bitcmp1_b32 s14, 0
	s_cselect_b32 s15, 0xf400, 0
	s_add_i32 s15, s15, 0
	v_add3_u32 v114, s15, v78, v79
	ds_read_b128 v[98:101], v114
	ds_read_b128 v[102:105], v114 offset:64
	ds_read_b128 v[106:109], v114 offset:128
	ds_read_b128 v[110:113], v114 offset:192
	v_cvt_pk_bf16_f32 v86, v4, v5
	v_cvt_pk_bf16_f32 v87, v6, v7
	v_cvt_pk_bf16_f32 v88, v28, v29
	v_cvt_pk_bf16_f32 v89, v30, v31
	v_cvt_pk_bf16_f32 v90, v32, v33
	v_cvt_pk_bf16_f32 v91, v34, v35
	v_cvt_pk_bf16_f32 v92, v12, v13
	v_cvt_pk_bf16_f32 v93, v14, v15
	v_cvt_pk_bf16_f32 v94, v20, v21
	v_cvt_pk_bf16_f32 v95, v22, v23
	v_cvt_pk_bf16_f32 v96, v8, v9
	v_cvt_pk_bf16_f32 v97, v10, v11
	v_cvt_pk_bf16_f32 v118, v24, v25
	v_cvt_pk_bf16_f32 v119, v26, v27
	v_cvt_pk_bf16_f32 v120, v16, v17
	v_cvt_pk_bf16_f32 v121, v18, v19
	ds_read_b128 v[122:125], v114 offset:17408
	ds_read_b128 v[126:129], v114 offset:17472
	ds_read_b128 v[130:133], v114 offset:17536
	ds_read_b128 v[134:137], v114 offset:17600
	s_waitcnt lgkmcnt(7)
	v_mfma_f32_16x16x32_bf16 v[64:67], v[98:101], v[86:89], v[64:67]
	s_waitcnt lgkmcnt(6)
	v_mfma_f32_16x16x32_bf16 v[64:67], v[102:105], v[90:93], v[64:67]
	s_waitcnt lgkmcnt(5)
	v_mfma_f32_16x16x32_bf16 v[64:67], v[106:109], v[94:97], v[64:67]
	s_waitcnt lgkmcnt(4)
	v_mfma_f32_16x16x32_bf16 v[64:67], v[110:113], v[118:121], v[64:67]
	ds_read_b128 v[98:101], v114 offset:4352
	ds_read_b128 v[102:105], v114 offset:4416
	ds_read_b128 v[106:109], v114 offset:4480
	ds_read_b128 v[110:113], v114 offset:4544
	s_waitcnt lgkmcnt(7)
	v_mfma_f32_16x16x32_bf16 v[122:125], v[122:125], v[86:89], 0
	s_waitcnt lgkmcnt(6)
	v_mfma_f32_16x16x32_bf16 v[122:125], v[126:129], v[90:93], v[122:125]
	s_waitcnt lgkmcnt(5)
	v_mfma_f32_16x16x32_bf16 v[122:125], v[130:133], v[94:97], v[122:125]
	s_waitcnt lgkmcnt(4)
	v_mfma_f32_16x16x32_bf16 v[122:125], v[134:137], v[118:121], v[122:125]
	ds_read_b128 v[126:129], v114 offset:21760
	ds_read_b128 v[130:133], v114 offset:21824
	ds_read_b128 v[134:137], v114 offset:21888
	ds_read_b128 v[138:141], v114 offset:21952
	s_waitcnt lgkmcnt(7)
	v_mfma_f32_16x16x32_bf16 v[60:63], v[98:101], v[86:89], v[60:63]
	s_waitcnt lgkmcnt(6)
	v_mfma_f32_16x16x32_bf16 v[60:63], v[102:105], v[90:93], v[60:63]
	s_waitcnt lgkmcnt(5)
	v_mfma_f32_16x16x32_bf16 v[60:63], v[106:109], v[94:97], v[60:63]
	s_waitcnt lgkmcnt(4)
	v_mfma_f32_16x16x32_bf16 v[60:63], v[110:113], v[118:121], v[60:63]
	ds_read_b128 v[98:101], v114 offset:8704
	ds_read_b128 v[102:105], v114 offset:8768
	ds_read_b128 v[106:109], v114 offset:8832
	ds_read_b128 v[110:113], v114 offset:8896
	s_waitcnt lgkmcnt(7)
	v_mfma_f32_16x16x32_bf16 v[126:129], v[126:129], v[86:89], 0
	s_waitcnt lgkmcnt(6)
	v_mfma_f32_16x16x32_bf16 v[126:129], v[130:133], v[90:93], v[126:129]
	s_waitcnt lgkmcnt(5)
	v_mfma_f32_16x16x32_bf16 v[126:129], v[134:137], v[94:97], v[126:129]
	s_waitcnt lgkmcnt(4)
	v_mfma_f32_16x16x32_bf16 v[126:129], v[138:141], v[118:121], v[126:129]
	ds_read_b128 v[130:133], v114 offset:26112
	ds_read_b128 v[134:137], v114 offset:26176
	ds_read_b128 v[138:141], v114 offset:26240
	ds_read_b128 v[146:149], v114 offset:26304
	s_waitcnt lgkmcnt(7)
	v_mfma_f32_16x16x32_bf16 v[56:59], v[98:101], v[86:89], v[56:59]
	s_waitcnt lgkmcnt(6)
	v_mfma_f32_16x16x32_bf16 v[56:59], v[102:105], v[90:93], v[56:59]
	s_waitcnt lgkmcnt(5)
	v_mfma_f32_16x16x32_bf16 v[56:59], v[106:109], v[94:97], v[56:59]
	s_waitcnt lgkmcnt(4)
	v_mfma_f32_16x16x32_bf16 v[56:59], v[110:113], v[118:121], v[56:59]
	v_add_u32_e32 v115, s15, v80
	v_add_u32_e32 v114, v115, v79
	ds_read_b128 v[98:101], v114
	ds_read_b128 v[102:105], v114 offset:64
	ds_read_b128 v[106:109], v114 offset:128
	ds_read_b128 v[110:113], v114 offset:192
	s_waitcnt lgkmcnt(7)
	v_mfma_f32_16x16x32_bf16 v[130:133], v[130:133], v[86:89], 0
	s_waitcnt lgkmcnt(6)
	v_mfma_f32_16x16x32_bf16 v[130:133], v[134:137], v[90:93], v[130:133]
	s_waitcnt lgkmcnt(5)
	v_mfma_f32_16x16x32_bf16 v[130:133], v[138:141], v[94:97], v[130:133]
	s_waitcnt lgkmcnt(4)
	v_mfma_f32_16x16x32_bf16 v[130:133], v[146:149], v[118:121], v[130:133]
	ds_read_b128 v[134:137], v114 offset:17408
	ds_read_b128 v[138:141], v114 offset:17472
	ds_read_b128 v[146:149], v114 offset:17536
	ds_read_b128 v[156:159], v114 offset:17600
	s_waitcnt lgkmcnt(7)
	v_mfma_f32_16x16x32_bf16 v[52:55], v[98:101], v[86:89], v[52:55]
	s_waitcnt lgkmcnt(6)
	v_mfma_f32_16x16x32_bf16 v[52:55], v[102:105], v[90:93], v[52:55]
	s_waitcnt lgkmcnt(5)
	v_mfma_f32_16x16x32_bf16 v[52:55], v[106:109], v[94:97], v[52:55]
	s_waitcnt lgkmcnt(4)
	v_mfma_f32_16x16x32_bf16 v[52:55], v[110:113], v[118:121], v[52:55]
	s_waitcnt lgkmcnt(3)
	v_mfma_f32_16x16x32_bf16 v[86:89], v[134:137], v[86:89], 0
	s_waitcnt lgkmcnt(2)
	v_mfma_f32_16x16x32_bf16 v[86:89], v[138:141], v[90:93], v[86:89]
	s_waitcnt lgkmcnt(1)
	v_mfma_f32_16x16x32_bf16 v[86:89], v[146:149], v[94:97], v[86:89]
	s_waitcnt lgkmcnt(0)
; #define LBAR() do { asm volatile("s_waitcnt lgkmcnt(0)" ::: "memory"); __builtin_amdgcn_s_barrier(); asm volatile("" ::: "memory"); } while (0)
; __device__ __forceinline__ bf16x8 packB(const f32x4& a, const f32x4& b) { u32x4 v = {pk2(a[0], a[1]), pk2(a[2], a[3]), pk2(b[0], b[1]), pk2(b[2], b[3])}; return __builtin_bit_cast(bf16x8, v); }
; #define SBAR() __builtin_amdgcn_sched_barrier(0)
; __device__ __forceinline__ void scan_bh(LAS unsigned char* lds, const ScanP& P, int b, int h, int half, int tid, int lane, int wave) {
;     ...
;         bf16x8 Ub[2];
;         Ub[0] = packB(u[0], u[1]); Ub[1] = packB(u[2], u[3]);
;         const float gl = __shfl(glv, n);
;     ...
;         {
;             bf16x8 aA[6], kA[4], kB[4];
;             aA[0] = frag1(Al + (0 * 16 + r) * TS + q8 * 8); aA[1] = frag1(Al + (1 * 16 + r) * TS + q8 * 8);
;             aA[2] = frag1(Al + (2 * 16 + r) * TS + q8 * 8); aA[3] = frag1(Al + (2 * 16 + r) * TS + 32 + q8 * 8);
;             aA[4] = frag1(Al + (3 * 16 + r) * TS + q8 * 8); aA[5] = frag1(Al + (3 * 16 + r) * TS + 32 + q8 * 8);
;             SBAR(); LDK(kA, 0); SBAR();
;             o[0] = __builtin_amdgcn_mfma_f32_16x16x32_bf16(aA[0], Ub[0], o[0], 0, 0, 0); o[1] = __builtin_amdgcn_mfma_f32_16x16x32_bf16(aA[1], Ub[0], o[1], 0, 0, 0);
;             o[2] = __builtin_amdgcn_mfma_f32_16x16x32_bf16(aA[2], Ub[0], o[2], 0, 0, 0); o[3] = __builtin_amdgcn_mfma_f32_16x16x32_bf16(aA[4], Ub[0], o[3], 0, 0, 0);
;             o[2] = __builtin_amdgcn_mfma_f32_16x16x32_bf16(aA[3], Ub[1], o[2], 0, 0, 0); o[3] = __builtin_amdgcn_mfma_f32_16x16x32_bf16(aA[5], Ub[1], o[3], 0, 0, 0);
;             SBAR(); LDK(kB, 2); SBAR(); MMK(kA, 0); SBAR(); LDK(kA, 4); SBAR(); MMK(kB, 2); SBAR(); LDK(kB, 6); SBAR(); MMK(kA, 4); SBAR(); MMK(kB, 6); SBAR();
;         }
;     ...
;         { unsigned oO = (unsigned)((q8 * 4) * 1024 + c0 + r) * 4u; asm volatile("" : "+v"(oO));
;           unsigned char* ob = (unsigned char*)(P.obuf + (size_t)(b * SEQ + n * 64) * 1024 + h * 128);
; #pragma unroll
;           for (int mt = 0; mt < 4; ++mt)
; #pragma unroll
;               for (int j = 0; j < 4; ++j) *(float*)(ob + (oO + (unsigned)(mt * 16 + j) * 4096u)) = o[mt][j]; }
;             LBAR();
	v_mfma_f32_16x16x32_bf16 v[86:89], v[156:159], v[118:121], v[86:89]
	v_cvt_pk_bf16_f32 v56, v56, v57
	v_cvt_pk_bf16_f32 v57, v58, v59
	v_cvt_pk_bf16_f32 v58, v52, v53
	v_lshlrev_b32_e32 v52, 2, v192
	v_and_b32_e32 v52, 0x100, v52
	v_add_u32_e32 v52, s10, v52
	v_add3_u32 v138, s15, v84, v85
	v_cvt_pk_bf16_f32 v64, v64, v65
	v_cvt_pk_bf16_f32 v65, v66, v67
	v_cvt_pk_bf16_f32 v66, v60, v61
	v_cvt_pk_bf16_f32 v67, v62, v63
	v_cvt_pk_bf16_f32 v59, v54, v55
	ds_bpermute_b32 v114, v52, v76
	ds_read_b128 v[52:55], v138 offset:34816
	ds_read_b128 v[60:63], v138 offset:37120
	ds_read_b128 v[90:93], v138 offset:39424
	ds_read_b128 v[94:97], v138 offset:39488
	v_add3_u32 v115, v115, v83, v85
	ds_read_b128 v[98:101], v115 offset:34816
	ds_read_b128 v[102:105], v115 offset:34880
	ds_read_b128 v[106:109], v138 offset:44032
	ds_read_b128 v[110:113], v138 offset:44096
	ds_read_b128 v[118:121], v138 offset:46336
	ds_read_b128 v[134:137], v138 offset:46400
	s_waitcnt lgkmcnt(9)
	v_mfma_f32_16x16x32_bf16 v[52:55], v[52:55], v[64:67], v[122:125]
	s_waitcnt lgkmcnt(8)
	v_mfma_f32_16x16x32_bf16 v[60:63], v[60:63], v[64:67], v[126:129]
	s_waitcnt lgkmcnt(7)
	v_mfma_f32_16x16x32_bf16 v[90:93], v[90:93], v[64:67], v[130:133]
	s_waitcnt lgkmcnt(5)
	v_mfma_f32_16x16x32_bf16 v[86:89], v[98:101], v[64:67], v[86:89]
	v_mfma_f32_16x16x32_bf16 v[90:93], v[94:97], v[56:59], v[90:93]
	s_waitcnt lgkmcnt(4)
	v_mfma_f32_16x16x32_bf16 v[86:89], v[102:105], v[56:59], v[86:89]
	ds_read_b128 v[94:97], v138 offset:48640
	ds_read_b128 v[98:101], v138 offset:48704
	ds_read_b128 v[102:105], v115 offset:44032
	ds_read_b128 v[122:125], v115 offset:44096
	v_pk_mul_f32 v[6:7], v[6:7], v[114:115] op_sel_hi:[1,0]
	v_pk_mul_f32 v[4:5], v[4:5], v[114:115] op_sel_hi:[1,0]
	v_pk_mul_f32 v[30:31], v[30:31], v[114:115] op_sel_hi:[1,0]
	v_pk_mul_f32 v[28:29], v[28:29], v[114:115] op_sel_hi:[1,0]
	s_waitcnt lgkmcnt(7)
	v_mfma_f32_16x16x32_bf16 v[4:7], v[106:109], v[64:67], v[4:7]
	s_waitcnt lgkmcnt(5)
	v_mfma_f32_16x16x32_bf16 v[28:31], v[118:121], v[64:67], v[28:31]
	v_mfma_f32_16x16x32_bf16 v[4:7], v[110:113], v[56:59], v[4:7]
	s_waitcnt lgkmcnt(4)
	v_mfma_f32_16x16x32_bf16 v[28:31], v[134:137], v[56:59], v[28:31]
	ds_read_b128 v[106:109], v138 offset:53248
	ds_read_b128 v[110:113], v138 offset:53312
	ds_read_b128 v[118:121], v138 offset:55552
	ds_read_b128 v[126:129], v138 offset:55616
	v_pk_mul_f32 v[34:35], v[34:35], v[114:115] op_sel_hi:[1,0]
	v_pk_mul_f32 v[32:33], v[32:33], v[114:115] op_sel_hi:[1,0]
	v_pk_mul_f32 v[14:15], v[14:15], v[114:115] op_sel_hi:[1,0]
	v_pk_mul_f32 v[12:13], v[12:13], v[114:115] op_sel_hi:[1,0]
	s_waitcnt lgkmcnt(7)
	v_mfma_f32_16x16x32_bf16 v[32:35], v[94:97], v[64:67], v[32:35]
	s_waitcnt lgkmcnt(5)
	v_mfma_f32_16x16x32_bf16 v[12:15], v[102:105], v[64:67], v[12:15]
	v_mfma_f32_16x16x32_bf16 v[32:35], v[98:101], v[56:59], v[32:35]
	s_waitcnt lgkmcnt(4)
	v_mfma_f32_16x16x32_bf16 v[12:15], v[122:125], v[56:59], v[12:15]
	v_add3_u32 v115, s15, v81, v85
	ds_read_b128 v[94:97], v138 offset:57856
	ds_read_b128 v[98:101], v138 offset:57920
	ds_read_b128 v[102:105], v115 offset:44032
	ds_read_b128 v[122:125], v115 offset:44096
	v_pk_mul_f32 v[22:23], v[22:23], v[114:115] op_sel_hi:[1,0]
	v_pk_mul_f32 v[20:21], v[20:21], v[114:115] op_sel_hi:[1,0]
	v_pk_mul_f32 v[10:11], v[10:11], v[114:115] op_sel_hi:[1,0]
	v_pk_mul_f32 v[8:9], v[8:9], v[114:115] op_sel_hi:[1,0]
	s_waitcnt lgkmcnt(7)
	v_mfma_f32_16x16x32_bf16 v[20:23], v[106:109], v[64:67], v[20:23]
	s_waitcnt lgkmcnt(5)
	v_mfma_f32_16x16x32_bf16 v[8:11], v[118:121], v[64:67], v[8:11]
	v_mfma_f32_16x16x32_bf16 v[20:23], v[110:113], v[56:59], v[20:23]
	s_waitcnt lgkmcnt(4)
	v_mfma_f32_16x16x32_bf16 v[8:11], v[126:129], v[56:59], v[8:11]
	v_mul_f32_e64 v26, v26, v114
	v_mul_f32_e64 v27, v27, v114
	v_pk_mul_f32 v[24:25], v[24:25], v[114:115] op_sel_hi:[1,0]
	v_pk_mul_f32 v[18:19], v[18:19], v[114:115] op_sel_hi:[1,0]
	v_pk_mul_f32 v[16:17], v[16:17], v[114:115] op_sel_hi:[1,0]
	s_waitcnt lgkmcnt(3)
	v_mfma_f32_16x16x32_bf16 v[24:27], v[94:97], v[64:67], v[24:27]
	s_waitcnt lgkmcnt(1)
	v_mfma_f32_16x16x32_bf16 v[16:19], v[102:105], v[64:67], v[16:19]
	v_mfma_f32_16x16x32_bf16 v[24:27], v[98:101], v[56:59], v[24:27]
	s_waitcnt lgkmcnt(0)
	v_mfma_f32_16x16x32_bf16 v[16:19], v[122:125], v[56:59], v[16:19]
	s_add_u32 s22, s24, s4
	s_addc_u32 s23, s25, s5
	v_mov_b64_e32 v[66:67], v[230:231]
	global_store_dword v236, v52, s[22:23]
	global_store_dword v237, v53, s[22:23]
	global_store_dword v238, v54, s[22:23]
	global_store_dword v239, v55, s[22:23]
	global_store_dword v240, v60, s[22:23]
	global_store_dword v241, v61, s[22:23]
	global_store_dword v242, v62, s[22:23]
	global_store_dword v243, v63, s[22:23]
	global_store_dword v244, v90, s[22:23]
	global_store_dword v245, v91, s[22:23]
	global_store_dword v246, v92, s[22:23]
	global_store_dword v247, v93, s[22:23]
	global_store_dword v248, v86, s[22:23]
	global_store_dword v249, v87, s[22:23]
	global_store_dword v250, v88, s[22:23]
	global_store_dword v251, v89, s[22:23]
	s_waitcnt lgkmcnt(0)
	s_barrier
	s_add_u32 s4, s4, 0x40000
	s_addc_u32 s5, s5, 0
	s_add_i32 s10, s10, 4
	s_add_i32 s11, s11, 8
	s_add_i32 s14, s14, 1
	v_mov_b64_e32 v[54:55], v[218:219]
	v_mov_b64_e32 v[58:59], v[222:223]
	v_mov_b64_e32 v[62:63], v[226:227]
	s_cmp_eq_u32 s4, 0x800000
	v_mov_b64_e32 v[52:53], v[216:217]
	v_mov_b64_e32 v[56:57], v[220:221]
	v_mov_b64_e32 v[60:61], v[224:225]
	v_mov_b64_e32 v[64:65], v[228:229]
; #define LAS __attribute__((address_space(3)))
; __device__ __forceinline__ bf16x8 packB(const f32x4& a, const f32x4& b) { u32x4 v = {pk2(a[0], a[1]), pk2(a[2], a[3]), pk2(b[0], b[1]), pk2(b[2], b[3])}; return __builtin_bit_cast(bf16x8, v); }
; #define U_LOAD(nn) do { const unsigned char* tr_ = P.tr + (size_t)((b << 8) | ((nn) << 3) | h) * TR_SZ; \
;             _Pragma("unroll") for (int mt_ = 0; mt_ < 4; ++mt_) ubn[mt_] = *(const f32x4*)(tr_ + (oU + (unsigned)mt_ * 1024u)); } while (0)
; #define SBAR() __builtin_amdgcn_sched_barrier(0)
; #define LD4(d, base, mt, stride) do { _Pragma("unroll") for (int ks = 0; ks < 4; ++ks) d[ks] = frag1((base) + ((mt) * 16 + r) * (stride) + ks * 32 + q8 * 8); } while (0)
; #define MM4(acc, s_) do { _Pragma("unroll") for (int ks = 0; ks < 4; ++ks) acc = __builtin_amdgcn_mfma_f32_16x16x32_bf16(s_[ks], Sb[ks], acc, 0, 0, 0); } while (0)
; __device__ __forceinline__ void scan_bh(LAS unsigned char* lds, const ScanP& P, int b, int h, int half, int tid, int lane, int wave) {
;     ...
;             LAS unsigned char* buf = lds + (n & 1) * SB_SZ;
;             const LAS bf16_t* Wl = (const LAS bf16_t*)(buf + SB_W); const LAS bf16_t* Ql = (const LAS bf16_t*)(buf + SB_Q);
;             const LAS bf16_t* Al = (const LAS bf16_t*)(buf + SB_A); const LAS bf16_t* Kl = (const LAS bf16_t*)(buf + SB_K);
;             f32x4 u[4], o[4];
; #pragma unroll
;             for (int mt = 0; mt < 4; ++mt) { u[mt] = ubn[mt]; o[mt] = (f32x4){0.f, 0.f, 0.f, 0.f}; }
;             if (n + 1 < 32) U_LOAD(n + 1);
;         bf16x8 Sb[4];
; #pragma unroll
;         for (int ks = 0; ks < 4; ++ks) Sb[ks] = packB(S[2 * ks], S[2 * ks + 1]);
;     ...
;         {
;             bf16x8 fA[4], fB[4];
;             LD4(fA, Wl, 0, PS); SBAR(); LD4(fB, Ql, 0, PS); SBAR();
;             MM4(u[0], fA); SBAR(); LD4(fA, Wl, 1, PS); SBAR(); MM4(o[0], fB); SBAR(); LD4(fB, Ql, 1, PS); SBAR();
;             MM4(u[1], fA); SBAR(); LD4(fA, Wl, 2, PS); SBAR(); MM4(o[1], fB); SBAR(); LD4(fB, Ql, 2, PS); SBAR();
;             MM4(u[2], fA); SBAR(); LD4(fA, Wl, 3, PS); SBAR(); MM4(o[2], fB); SBAR(); LD4(fB, Ql, 3, PS); SBAR();
;             MM4(u[3], fA); SBAR(); MM4(o[3], fB); SBAR();
;         }
.Lscan_c3:
	s_add_i32 s15, s11, 24
	s_min_u32 s15, s15, 0xf8
	s_or_b32 s15, s15, s6
	v_mad_i64_i32 v[44:45], s[16:17], s15, v199, v[116:117]
	v_lshl_add_u64 v[36:37], v[44:45], 0, v[74:75]
	v_lshl_add_u64 v[38:39], v[44:45], 0, v[72:73]
	v_lshl_add_u64 v[46:47], v[44:45], 0, v[70:71]
	v_lshl_add_u64 v[44:45], v[44:45], 0, v[68:69]
	global_load_dwordx4 v[216:219], v[36:37], off
	global_load_dwordx4 v[220:223], v[38:39], off
	global_load_dwordx4 v[224:227], v[46:47], off
	global_load_dwordx4 v[228:231], v[44:45], off
	s_waitcnt vmcnt(60)
	s_bitcmp1_b32 s14, 0
	s_cselect_b32 s15, 0xf400, 0
	s_add_i32 s15, s15, 0
	v_add3_u32 v114, s15, v78, v79
	ds_read_b128 v[98:101], v114
	ds_read_b128 v[102:105], v114 offset:64
	ds_read_b128 v[106:109], v114 offset:128
	ds_read_b128 v[110:113], v114 offset:192
	v_cvt_pk_bf16_f32 v86, v4, v5
	v_cvt_pk_bf16_f32 v87, v6, v7
	v_cvt_pk_bf16_f32 v88, v28, v29
	v_cvt_pk_bf16_f32 v89, v30, v31
	v_cvt_pk_bf16_f32 v90, v32, v33
	v_cvt_pk_bf16_f32 v91, v34, v35
	v_cvt_pk_bf16_f32 v92, v12, v13
	v_cvt_pk_bf16_f32 v93, v14, v15
	v_cvt_pk_bf16_f32 v94, v20, v21
	v_cvt_pk_bf16_f32 v95, v22, v23
	v_cvt_pk_bf16_f32 v96, v8, v9
	v_cvt_pk_bf16_f32 v97, v10, v11
	v_cvt_pk_bf16_f32 v118, v24, v25
	v_cvt_pk_bf16_f32 v119, v26, v27
	v_cvt_pk_bf16_f32 v120, v16, v17
	v_cvt_pk_bf16_f32 v121, v18, v19
	ds_read_b128 v[122:125], v114 offset:17408
	ds_read_b128 v[126:129], v114 offset:17472
	ds_read_b128 v[130:133], v114 offset:17536
	ds_read_b128 v[134:137], v114 offset:17600
	s_waitcnt lgkmcnt(7)
	v_mfma_f32_16x16x32_bf16 v[64:67], v[98:101], v[86:89], v[64:67]
	s_waitcnt lgkmcnt(6)
	v_mfma_f32_16x16x32_bf16 v[64:67], v[102:105], v[90:93], v[64:67]
	s_waitcnt lgkmcnt(5)
	v_mfma_f32_16x16x32_bf16 v[64:67], v[106:109], v[94:97], v[64:67]
	s_waitcnt lgkmcnt(4)
	v_mfma_f32_16x16x32_bf16 v[64:67], v[110:113], v[118:121], v[64:67]
	ds_read_b128 v[98:101], v114 offset:4352
	ds_read_b128 v[102:105], v114 offset:4416
	ds_read_b128 v[106:109], v114 offset:4480
	ds_read_b128 v[110:113], v114 offset:4544
	s_waitcnt lgkmcnt(7)
	v_mfma_f32_16x16x32_bf16 v[122:125], v[122:125], v[86:89], 0
	s_waitcnt lgkmcnt(6)
	v_mfma_f32_16x16x32_bf16 v[122:125], v[126:129], v[90:93], v[122:125]
	s_waitcnt lgkmcnt(5)
	v_mfma_f32_16x16x32_bf16 v[122:125], v[130:133], v[94:97], v[122:125]
	s_waitcnt lgkmcnt(4)
	v_mfma_f32_16x16x32_bf16 v[122:125], v[134:137], v[118:121], v[122:125]
	ds_read_b128 v[126:129], v114 offset:21760
	ds_read_b128 v[130:133], v114 offset:21824
	ds_read_b128 v[134:137], v114 offset:21888
	ds_read_b128 v[138:141], v114 offset:21952
	s_waitcnt lgkmcnt(7)
	v_mfma_f32_16x16x32_bf16 v[60:63], v[98:101], v[86:89], v[60:63]
	s_waitcnt lgkmcnt(6)
	v_mfma_f32_16x16x32_bf16 v[60:63], v[102:105], v[90:93], v[60:63]
	s_waitcnt lgkmcnt(5)
	v_mfma_f32_16x16x32_bf16 v[60:63], v[106:109], v[94:97], v[60:63]
	s_waitcnt lgkmcnt(4)
	v_mfma_f32_16x16x32_bf16 v[60:63], v[110:113], v[118:121], v[60:63]
	ds_read_b128 v[98:101], v114 offset:8704
	ds_read_b128 v[102:105], v114 offset:8768
	ds_read_b128 v[106:109], v114 offset:8832
	ds_read_b128 v[110:113], v114 offset:8896
	s_waitcnt lgkmcnt(7)
	v_mfma_f32_16x16x32_bf16 v[126:129], v[126:129], v[86:89], 0
	s_waitcnt lgkmcnt(6)
	v_mfma_f32_16x16x32_bf16 v[126:129], v[130:133], v[90:93], v[126:129]
	s_waitcnt lgkmcnt(5)
	v_mfma_f32_16x16x32_bf16 v[126:129], v[134:137], v[94:97], v[126:129]
	s_waitcnt lgkmcnt(4)
	v_mfma_f32_16x16x32_bf16 v[126:129], v[138:141], v[118:121], v[126:129]
	ds_read_b128 v[130:133], v114 offset:26112
	ds_read_b128 v[134:137], v114 offset:26176
	ds_read_b128 v[138:141], v114 offset:26240
	ds_read_b128 v[146:149], v114 offset:26304
	s_waitcnt lgkmcnt(7)
	v_mfma_f32_16x16x32_bf16 v[56:59], v[98:101], v[86:89], v[56:59]
	s_waitcnt lgkmcnt(6)
	v_mfma_f32_16x16x32_bf16 v[56:59], v[102:105], v[90:93], v[56:59]
	s_waitcnt lgkmcnt(5)
	v_mfma_f32_16x16x32_bf16 v[56:59], v[106:109], v[94:97], v[56:59]
	s_waitcnt lgkmcnt(4)
	v_mfma_f32_16x16x32_bf16 v[56:59], v[110:113], v[118:121], v[56:59]
	v_add_u32_e32 v115, s15, v80
	v_add_u32_e32 v114, v115, v79
	ds_read_b128 v[98:101], v114
	ds_read_b128 v[102:105], v114 offset:64
	ds_read_b128 v[106:109], v114 offset:128
	ds_read_b128 v[110:113], v114 offset:192
	s_waitcnt lgkmcnt(7)
	v_mfma_f32_16x16x32_bf16 v[130:133], v[130:133], v[86:89], 0
	s_waitcnt lgkmcnt(6)
	v_mfma_f32_16x16x32_bf16 v[130:133], v[134:137], v[90:93], v[130:133]
	s_waitcnt lgkmcnt(5)
	v_mfma_f32_16x16x32_bf16 v[130:133], v[138:141], v[94:97], v[130:133]
	s_waitcnt lgkmcnt(4)
	v_mfma_f32_16x16x32_bf16 v[130:133], v[146:149], v[118:121], v[130:133]
	ds_read_b128 v[134:137], v114 offset:17408
	ds_read_b128 v[138:141], v114 offset:17472
	ds_read_b128 v[146:149], v114 offset:17536
	ds_read_b128 v[156:159], v114 offset:17600
	s_waitcnt lgkmcnt(7)
	v_mfma_f32_16x16x32_bf16 v[52:55], v[98:101], v[86:89], v[52:55]
	s_waitcnt lgkmcnt(6)
	v_mfma_f32_16x16x32_bf16 v[52:55], v[102:105], v[90:93], v[52:55]
	s_waitcnt lgkmcnt(5)
	v_mfma_f32_16x16x32_bf16 v[52:55], v[106:109], v[94:97], v[52:55]
	s_waitcnt lgkmcnt(4)
	v_mfma_f32_16x16x32_bf16 v[52:55], v[110:113], v[118:121], v[52:55]
	s_waitcnt lgkmcnt(3)
	v_mfma_f32_16x16x32_bf16 v[86:89], v[134:137], v[86:89], 0
	s_waitcnt lgkmcnt(2)
	v_mfma_f32_16x16x32_bf16 v[86:89], v[138:141], v[90:93], v[86:89]
	s_waitcnt lgkmcnt(1)
	v_mfma_f32_16x16x32_bf16 v[86:89], v[146:149], v[94:97], v[86:89]
	s_waitcnt lgkmcnt(0)
; #define LBAR() do { asm volatile("s_waitcnt lgkmcnt(0)" ::: "memory"); __builtin_amdgcn_s_barrier(); asm volatile("" ::: "memory"); } while (0)
; __device__ __forceinline__ bf16x8 packB(const f32x4& a, const f32x4& b) { u32x4 v = {pk2(a[0], a[1]), pk2(a[2], a[3]), pk2(b[0], b[1]), pk2(b[2], b[3])}; return __builtin_bit_cast(bf16x8, v); }
; #define SBAR() __builtin_amdgcn_sched_barrier(0)
; __device__ __forceinline__ void scan_bh(LAS unsigned char* lds, const ScanP& P, int b, int h, int half, int tid, int lane, int wave) {
;     ...
;         bf16x8 Ub[2];
;         Ub[0] = packB(u[0], u[1]); Ub[1] = packB(u[2], u[3]);
;         const float gl = __shfl(glv, n);
;     ...
;         {
;             bf16x8 aA[6], kA[4], kB[4];
;             aA[0] = frag1(Al + (0 * 16 + r) * TS + q8 * 8); aA[1] = frag1(Al + (1 * 16 + r) * TS + q8 * 8);
;             aA[2] = frag1(Al + (2 * 16 + r) * TS + q8 * 8); aA[3] = frag1(Al + (2 * 16 + r) * TS + 32 + q8 * 8);
;             aA[4] = frag1(Al + (3 * 16 + r) * TS + q8 * 8); aA[5] = frag1(Al + (3 * 16 + r) * TS + 32 + q8 * 8);
;             SBAR(); LDK(kA, 0); SBAR();
;             o[0] = __builtin_amdgcn_mfma_f32_16x16x32_bf16(aA[0], Ub[0], o[0], 0, 0, 0); o[1] = __builtin_amdgcn_mfma_f32_16x16x32_bf16(aA[1], Ub[0], o[1], 0, 0, 0);
;             o[2] = __builtin_amdgcn_mfma_f32_16x16x32_bf16(aA[2], Ub[0], o[2], 0, 0, 0); o[3] = __builtin_amdgcn_mfma_f32_16x16x32_bf16(aA[4], Ub[0], o[3], 0, 0, 0);
;             o[2] = __builtin_amdgcn_mfma_f32_16x16x32_bf16(aA[3], Ub[1], o[2], 0, 0, 0); o[3] = __builtin_amdgcn_mfma_f32_16x16x32_bf16(aA[5], Ub[1], o[3], 0, 0, 0);
;             SBAR(); LDK(kB, 2); SBAR(); MMK(kA, 0); SBAR(); LDK(kA, 4); SBAR(); MMK(kB, 2); SBAR(); LDK(kB, 6); SBAR(); MMK(kA, 4); SBAR(); MMK(kB, 6); SBAR();
;         }
;     ...
;         { unsigned oO = (unsigned)((q8 * 4) * 1024 + c0 + r) * 4u; asm volatile("" : "+v"(oO));
;           unsigned char* ob = (unsigned char*)(P.obuf + (size_t)(b * SEQ + n * 64) * 1024 + h * 128);
; #pragma unroll
;           for (int mt = 0; mt < 4; ++mt)
; #pragma unroll
;               for (int j = 0; j < 4; ++j) *(float*)(ob + (oO + (unsigned)(mt * 16 + j) * 4096u)) = o[mt][j]; }
;             LBAR();
	v_mfma_f32_16x16x32_bf16 v[86:89], v[156:159], v[118:121], v[86:89]
	v_cvt_pk_bf16_f32 v56, v56, v57
	v_cvt_pk_bf16_f32 v57, v58, v59
	v_cvt_pk_bf16_f32 v58, v52, v53
	v_lshlrev_b32_e32 v52, 2, v192
	v_and_b32_e32 v52, 0x100, v52
	v_add_u32_e32 v52, s10, v52
	v_add3_u32 v138, s15, v84, v85
	v_cvt_pk_bf16_f32 v64, v64, v65
	v_cvt_pk_bf16_f32 v65, v66, v67
	v_cvt_pk_bf16_f32 v66, v60, v61
	v_cvt_pk_bf16_f32 v67, v62, v63
	v_cvt_pk_bf16_f32 v59, v54, v55
	ds_bpermute_b32 v114, v52, v76
	ds_read_b128 v[52:55], v138 offset:34816
	ds_read_b128 v[60:63], v138 offset:37120
	ds_read_b128 v[90:93], v138 offset:39424
	ds_read_b128 v[94:97], v138 offset:39488
	v_add3_u32 v115, v115, v83, v85
	ds_read_b128 v[98:101], v115 offset:34816
	ds_read_b128 v[102:105], v115 offset:34880
	ds_read_b128 v[106:109], v138 offset:44032
	ds_read_b128 v[110:113], v138 offset:44096
	ds_read_b128 v[118:121], v138 offset:46336
	ds_read_b128 v[134:137], v138 offset:46400
	s_waitcnt lgkmcnt(9)
	v_mfma_f32_16x16x32_bf16 v[52:55], v[52:55], v[64:67], v[122:125]
	s_waitcnt lgkmcnt(8)
	v_mfma_f32_16x16x32_bf16 v[60:63], v[60:63], v[64:67], v[126:129]
	s_waitcnt lgkmcnt(7)
	v_mfma_f32_16x16x32_bf16 v[90:93], v[90:93], v[64:67], v[130:133]
	s_waitcnt lgkmcnt(5)
	v_mfma_f32_16x16x32_bf16 v[86:89], v[98:101], v[64:67], v[86:89]
	v_mfma_f32_16x16x32_bf16 v[90:93], v[94:97], v[56:59], v[90:93]
	s_waitcnt lgkmcnt(4)
	v_mfma_f32_16x16x32_bf16 v[86:89], v[102:105], v[56:59], v[86:89]
	ds_read_b128 v[94:97], v138 offset:48640
	ds_read_b128 v[98:101], v138 offset:48704
	ds_read_b128 v[102:105], v115 offset:44032
	ds_read_b128 v[122:125], v115 offset:44096
	v_pk_mul_f32 v[6:7], v[6:7], v[114:115] op_sel_hi:[1,0]
	v_pk_mul_f32 v[4:5], v[4:5], v[114:115] op_sel_hi:[1,0]
	v_pk_mul_f32 v[30:31], v[30:31], v[114:115] op_sel_hi:[1,0]
	v_pk_mul_f32 v[28:29], v[28:29], v[114:115] op_sel_hi:[1,0]
	s_waitcnt lgkmcnt(7)
	v_mfma_f32_16x16x32_bf16 v[4:7], v[106:109], v[64:67], v[4:7]
	s_waitcnt lgkmcnt(5)
	v_mfma_f32_16x16x32_bf16 v[28:31], v[118:121], v[64:67], v[28:31]
	v_mfma_f32_16x16x32_bf16 v[4:7], v[110:113], v[56:59], v[4:7]
	s_waitcnt lgkmcnt(4)
	v_mfma_f32_16x16x32_bf16 v[28:31], v[134:137], v[56:59], v[28:31]
	ds_read_b128 v[106:109], v138 offset:53248
	ds_read_b128 v[110:113], v138 offset:53312
	ds_read_b128 v[118:121], v138 offset:55552
	ds_read_b128 v[126:129], v138 offset:55616
	v_pk_mul_f32 v[34:35], v[34:35], v[114:115] op_sel_hi:[1,0]
	v_pk_mul_f32 v[32:33], v[32:33], v[114:115] op_sel_hi:[1,0]
	v_pk_mul_f32 v[14:15], v[14:15], v[114:115] op_sel_hi:[1,0]
	v_pk_mul_f32 v[12:13], v[12:13], v[114:115] op_sel_hi:[1,0]
	s_waitcnt lgkmcnt(7)
	v_mfma_f32_16x16x32_bf16 v[32:35], v[94:97], v[64:67], v[32:35]
	s_waitcnt lgkmcnt(5)
	v_mfma_f32_16x16x32_bf16 v[12:15], v[102:105], v[64:67], v[12:15]
	v_mfma_f32_16x16x32_bf16 v[32:35], v[98:101], v[56:59], v[32:35]
	s_waitcnt lgkmcnt(4)
	v_mfma_f32_16x16x32_bf16 v[12:15], v[122:125], v[56:59], v[12:15]
	v_add3_u32 v115, s15, v81, v85
	ds_read_b128 v[94:97], v138 offset:57856
	ds_read_b128 v[98:101], v138 offset:57920
	ds_read_b128 v[102:105], v115 offset:44032
	ds_read_b128 v[122:125], v115 offset:44096
	v_pk_mul_f32 v[22:23], v[22:23], v[114:115] op_sel_hi:[1,0]
	v_pk_mul_f32 v[20:21], v[20:21], v[114:115] op_sel_hi:[1,0]
	v_pk_mul_f32 v[10:11], v[10:11], v[114:115] op_sel_hi:[1,0]
	v_pk_mul_f32 v[8:9], v[8:9], v[114:115] op_sel_hi:[1,0]
	s_waitcnt lgkmcnt(7)
	v_mfma_f32_16x16x32_bf16 v[20:23], v[106:109], v[64:67], v[20:23]
	s_waitcnt lgkmcnt(5)
	v_mfma_f32_16x16x32_bf16 v[8:11], v[118:121], v[64:67], v[8:11]
	v_mfma_f32_16x16x32_bf16 v[20:23], v[110:113], v[56:59], v[20:23]
	s_waitcnt lgkmcnt(4)
	v_mfma_f32_16x16x32_bf16 v[8:11], v[126:129], v[56:59], v[8:11]
	v_mul_f32_e64 v26, v26, v114
	v_mul_f32_e64 v27, v27, v114
	v_pk_mul_f32 v[24:25], v[24:25], v[114:115] op_sel_hi:[1,0]
	v_pk_mul_f32 v[18:19], v[18:19], v[114:115] op_sel_hi:[1,0]
	v_pk_mul_f32 v[16:17], v[16:17], v[114:115] op_sel_hi:[1,0]
	s_waitcnt lgkmcnt(3)
	v_mfma_f32_16x16x32_bf16 v[24:27], v[94:97], v[64:67], v[24:27]
	s_waitcnt lgkmcnt(1)
	v_mfma_f32_16x16x32_bf16 v[16:19], v[102:105], v[64:67], v[16:19]
	v_mfma_f32_16x16x32_bf16 v[24:27], v[98:101], v[56:59], v[24:27]
	s_waitcnt lgkmcnt(0)
	v_mfma_f32_16x16x32_bf16 v[16:19], v[122:125], v[56:59], v[16:19]
	s_add_u32 s22, s24, s4
	s_addc_u32 s23, s25, s5
	v_mov_b64_e32 v[66:67], v[174:175]
	global_store_dword v236, v52, s[22:23]
	global_store_dword v237, v53, s[22:23]
	global_store_dword v238, v54, s[22:23]
	global_store_dword v239, v55, s[22:23]
	global_store_dword v240, v60, s[22:23]
	global_store_dword v241, v61, s[22:23]
	global_store_dword v242, v62, s[22:23]
	global_store_dword v243, v63, s[22:23]
	global_store_dword v244, v90, s[22:23]
	global_store_dword v245, v91, s[22:23]
	global_store_dword v246, v92, s[22:23]
	global_store_dword v247, v93, s[22:23]
	global_store_dword v248, v86, s[22:23]
	global_store_dword v249, v87, s[22:23]
	global_store_dword v250, v88, s[22:23]
	global_store_dword v251, v89, s[22:23]
	s_waitcnt lgkmcnt(0)
	s_barrier
	s_add_u32 s4, s4, 0x40000
	s_addc_u32 s5, s5, 0
	s_add_i32 s10, s10, 4
	s_add_i32 s11, s11, 8
	s_add_i32 s14, s14, 1
	v_mov_b64_e32 v[54:55], v[162:163]
	v_mov_b64_e32 v[58:59], v[166:167]
	v_mov_b64_e32 v[62:63], v[170:171]
	s_cmp_eq_u32 s4, 0x800000
	v_mov_b64_e32 v[52:53], v[160:161]
	v_mov_b64_e32 v[56:57], v[164:165]
	v_mov_b64_e32 v[60:61], v[168:169]
	v_mov_b64_e32 v[64:65], v[172:173]
	s_cbranch_scc0 .Lscan_c0
